# per-cluster s_setprio 1/0 flips replaced by s_nop in the four K=256 GEMMs (U item and the three mout GEMMs); on top of v64
# speedup vs baseline: 1.0032x; 1.0006x over previous
.Lpadskip_3:
.LBB0_402:
	s_add_i32 s36, s93, s33
	s_lshl_b32 s3, s3, 12
	v_lshl_add_u64 v[16:17], v[12:13], 0, s[70:71]
	s_mov_b32 m0, s36
	s_add_i32 s19, s36, 0x2000
	s_lshl_b32 s10, s2, 13
	s_and_b32 s11, s3, 0x3000
	s_waitcnt vmcnt(4)
	s_barrier
	global_load_lds_dwordx4 v[16:17], off
	v_lshl_add_u64 v[16:17], v[10:11], 0, s[70:71]
	s_mov_b32 m0, s19
	s_add_i32 s16, s41, 0x8000
	s_add_i32 s15, s41, 0xa000
	global_load_lds_dwordx4 v[16:17], off
	v_lshl_add_u64 v[16:17], v[6:7], 0, s[70:71]
	s_mov_b32 m0, s16
	s_add_u32 s6, s4, 0x10080
	global_load_lds_dwordx4 v[16:17], off
	v_lshl_add_u64 v[16:17], v[8:9], 0, s[70:71]
	s_mov_b32 m0, s15
	s_addc_u32 s7, s5, 0
	s_add_i32 s2, s94, s33
	global_load_lds_dwordx4 v[16:17], off
	v_lshl_add_u64 v[16:17], s[6:7], 0, v[128:129]
	s_mov_b32 m0, s2
	s_add_i32 s3, s2, 0x2000
	global_load_lds_dwordx4 v[16:17], off
	v_lshl_add_u64 v[16:17], s[6:7], 0, v[4:5]
	s_mov_b32 m0, s3
	v_and_b32_e32 v15, 15, v14
	global_load_lds_dwordx4 v[16:17], off
	v_and_b32_e32 v16, 48, v14
	v_lshlrev_b32_e32 v14, 2, v14
	v_lshlrev_b32_e32 v15, 6, v15
	v_and_b32_e32 v14, 32, v14
	v_or_b32_e32 v17, v15, v16
	v_bitop3_b32 v15, v15, v14, v16 bitop3:0x36
	v_or_b32_e32 v64, s11, v15
	s_add_i32 s43, 0, 0x10000
	v_bitop3_b32 v14, v17, s10, v14 bitop3:0xde
	v_add_u32_e32 v131, s43, v64
	s_waitcnt vmcnt(6)
	s_barrier
	s_add_u32 s48, s8, 0x10080
	v_add_u32_e32 v183, 0, v14
	ds_read_b128 v[14:17], v131
	ds_read_b128 v[18:21], v131 offset:1024
	ds_read_b128 v[22:25], v131 offset:2048
	ds_read_b128 v[26:29], v131 offset:3072
	s_addc_u32 s49, s9, 0
	s_add_i32 s50, 0, 0x14000
	s_add_u32 s12, s4, 0x10100
	s_addc_u32 s13, s5, 0
	s_add_u32 s10, s8, 0x10100
	s_addc_u32 s11, s9, 0
	s_add_u32 s6, s4, 0x10180
	v_add_u32_e32 v144, s50, v64
	s_addc_u32 s7, s5, 0
	s_add_i32 s17, s41, 0xc000
	v_lshl_add_u64 v[62:63], s[48:49], 0, v[0:1]
	s_mov_b32 m0, s17
	s_add_i32 s14, s41, 0xe000
	ds_read_b128 v[30:33], v183
	ds_read_b128 v[34:37], v183 offset:1024
	ds_read_b128 v[38:41], v183 offset:2048
	ds_read_b128 v[42:45], v183 offset:3072
	ds_read_b128 v[46:49], v183 offset:4096
	ds_read_b128 v[50:53], v183 offset:5120
	ds_read_b128 v[54:57], v183 offset:6144
	ds_read_b128 v[58:61], v183 offset:7168
	global_load_lds_dwordx4 v[62:63], off
	v_lshl_add_u64 v[62:63], s[48:49], 0, v[2:3]
	s_mov_b32 m0, s14
	v_add_u32_e32 v145, s93, v64
	global_load_lds_dwordx4 v[62:63], off
	s_waitcnt lgkmcnt(8)
	s_barrier
	s_waitcnt lgkmcnt(0)
	v_add_u32_e32 v146, s94, v64
	s_nop 0
	s_waitcnt lgkmcnt(0)
	v_mfma_f32_16x16x32_bf16 v[62:65], v[14:17], v[30:33], 0
	v_mfma_f32_16x16x32_bf16 v[66:69], v[22:25], v[30:33], 0
	v_mfma_f32_16x16x32_bf16 v[70:73], v[14:17], v[38:41], 0
	v_mfma_f32_16x16x32_bf16 v[74:77], v[22:25], v[38:41], 0
	v_mfma_f32_16x16x32_bf16 v[78:81], v[14:17], v[46:49], 0
	v_mfma_f32_16x16x32_bf16 v[82:85], v[22:25], v[46:49], 0
	v_mfma_f32_16x16x32_bf16 v[86:89], v[14:17], v[54:57], 0
	v_mfma_f32_16x16x32_bf16 v[90:93], v[22:25], v[54:57], 0
	v_mfma_f32_16x16x32_bf16 v[62:65], v[18:21], v[34:37], v[62:65]
	v_mfma_f32_16x16x32_bf16 v[66:69], v[26:29], v[34:37], v[66:69]
	v_mfma_f32_16x16x32_bf16 v[70:73], v[18:21], v[42:45], v[70:73]
	v_mfma_f32_16x16x32_bf16 v[74:77], v[26:29], v[42:45], v[74:77]
	v_mfma_f32_16x16x32_bf16 v[78:81], v[18:21], v[50:53], v[78:81]
	v_mfma_f32_16x16x32_bf16 v[82:85], v[26:29], v[50:53], v[82:85]
	v_mfma_f32_16x16x32_bf16 v[86:89], v[18:21], v[58:61], v[86:89]
	v_mfma_f32_16x16x32_bf16 v[90:93], v[26:29], v[58:61], v[90:93]
	s_nop 0
	s_barrier
	s_add_i32 s43, s43, s33
	v_lshl_add_u64 v[110:111], v[12:13], 0, s[72:73]
	s_mov_b32 m0, s43
	ds_read_b128 v[94:97], v144
	ds_read_b128 v[98:101], v144 offset:1024
	ds_read_b128 v[102:105], v144 offset:2048
	ds_read_b128 v[106:109], v144 offset:3072
	global_load_lds_dwordx4 v[110:111], off
	v_lshl_add_u64 v[110:111], v[10:11], 0, s[72:73]
	s_add_i32 m0, s43, 0x2000
	s_nop 0
	global_load_lds_dwordx4 v[110:111], off
	s_barrier
	s_waitcnt lgkmcnt(0)
	s_nop 0
	s_waitcnt lgkmcnt(0)
	v_mfma_f32_16x16x32_bf16 v[110:113], v[94:97], v[30:33], 0
	v_mfma_f32_16x16x32_bf16 v[30:33], v[102:105], v[30:33], 0
	v_mfma_f32_16x16x32_bf16 v[110:113], v[98:101], v[34:37], v[110:113]
	v_mfma_f32_16x16x32_bf16 v[30:33], v[106:109], v[34:37], v[30:33]
	v_mfma_f32_16x16x32_bf16 v[34:37], v[94:97], v[38:41], 0
	v_mfma_f32_16x16x32_bf16 v[38:41], v[102:105], v[38:41], 0
	v_mfma_f32_16x16x32_bf16 v[34:37], v[98:101], v[42:45], v[34:37]
	v_mfma_f32_16x16x32_bf16 v[38:41], v[106:109], v[42:45], v[38:41]
	v_mfma_f32_16x16x32_bf16 v[42:45], v[94:97], v[46:49], 0
	v_mfma_f32_16x16x32_bf16 v[46:49], v[102:105], v[46:49], 0
	v_mfma_f32_16x16x32_bf16 v[42:45], v[98:101], v[50:53], v[42:45]
	v_mfma_f32_16x16x32_bf16 v[46:49], v[106:109], v[50:53], v[46:49]
	v_mfma_f32_16x16x32_bf16 v[50:53], v[94:97], v[54:57], 0
	v_mfma_f32_16x16x32_bf16 v[54:57], v[102:105], v[54:57], 0
	v_mfma_f32_16x16x32_bf16 v[50:53], v[98:101], v[58:61], v[50:53]
	v_mfma_f32_16x16x32_bf16 v[54:57], v[106:109], v[58:61], v[54:57]
	s_nop 0
	s_mov_b32 m0, s41
	v_lshl_add_u64 v[126:127], v[6:7], 0, s[72:73]
	s_barrier
	ds_read_b128 v[58:61], v183 offset:16384
	ds_read_b128 v[114:117], v183 offset:17408
	ds_read_b128 v[118:121], v183 offset:18432
	ds_read_b128 v[122:125], v183 offset:19456
	ds_read_b128 v[132:135], v183 offset:20480
	ds_read_b128 v[136:139], v183 offset:21504
	ds_read_b128 v[140:143], v183 offset:22528
	ds_read_b128 v[152:155], v183 offset:23552
	global_load_lds_dwordx4 v[126:127], off
	v_lshl_add_u64 v[126:127], v[8:9], 0, s[72:73]
	s_mov_b32 m0, s42
	s_nop 0
	global_load_lds_dwordx4 v[126:127], off
	s_barrier
	s_waitcnt lgkmcnt(0)
	s_nop 0
	s_waitcnt lgkmcnt(0)
	v_mfma_f32_16x16x32_bf16 v[156:159], v[14:17], v[58:61], 0
	v_mfma_f32_16x16x32_bf16 v[164:167], v[14:17], v[118:121], 0
	v_mfma_f32_16x16x32_bf16 v[172:175], v[14:17], v[132:135], 0
	v_mfma_f32_16x16x32_bf16 v[14:17], v[14:17], v[140:143], 0
	v_mfma_f32_16x16x32_bf16 v[156:159], v[18:21], v[114:117], v[156:159]
	v_mfma_f32_16x16x32_bf16 v[164:167], v[18:21], v[122:125], v[164:167]
	v_mfma_f32_16x16x32_bf16 v[172:175], v[18:21], v[136:139], v[172:175]
	v_mfma_f32_16x16x32_bf16 v[14:17], v[18:21], v[152:155], v[14:17]
	v_mfma_f32_16x16x32_bf16 v[18:21], v[22:25], v[140:143], 0
	v_mfma_f32_16x16x32_bf16 v[160:163], v[22:25], v[58:61], 0
	v_mfma_f32_16x16x32_bf16 v[168:171], v[22:25], v[118:121], 0
	v_mfma_f32_16x16x32_bf16 v[176:179], v[22:25], v[132:135], 0
	v_mfma_f32_16x16x32_bf16 v[18:21], v[26:29], v[152:155], v[18:21]
	v_mfma_f32_16x16x32_bf16 v[160:163], v[26:29], v[114:117], v[160:163]
	v_mfma_f32_16x16x32_bf16 v[168:171], v[26:29], v[122:125], v[168:171]
	v_mfma_f32_16x16x32_bf16 v[176:179], v[26:29], v[136:139], v[176:179]
	s_nop 0
	s_barrier
	s_add_i32 s33, s50, s33
	v_lshl_add_u64 v[22:23], s[12:13], 0, v[128:129]
	s_mov_b32 m0, s33
	s_nop 0
	global_load_lds_dwordx4 v[22:23], off
	v_lshl_add_u64 v[22:23], s[12:13], 0, v[4:5]
	s_add_i32 m0, s33, 0x2000
	s_nop 0
	global_load_lds_dwordx4 v[22:23], off
	s_waitcnt vmcnt(6)
	s_barrier
	s_nop 0
	v_mfma_f32_16x16x32_bf16 v[22:25], v[94:97], v[58:61], 0
	v_mfma_f32_16x16x32_bf16 v[26:29], v[102:105], v[58:61], 0
	v_mfma_f32_16x16x32_bf16 v[22:25], v[98:101], v[114:117], v[22:25]
	v_mfma_f32_16x16x32_bf16 v[26:29], v[106:109], v[114:117], v[26:29]
	v_mfma_f32_16x16x32_bf16 v[58:61], v[94:97], v[118:121], 0
	v_mfma_f32_16x16x32_bf16 v[114:117], v[102:105], v[118:121], 0
	v_mfma_f32_16x16x32_bf16 v[118:121], v[94:97], v[132:135], 0
	v_mfma_f32_16x16x32_bf16 v[94:97], v[94:97], v[140:143], 0
	v_mfma_f32_16x16x32_bf16 v[58:61], v[98:101], v[122:125], v[58:61]
	v_mfma_f32_16x16x32_bf16 v[114:117], v[106:109], v[122:125], v[114:117]
	v_mfma_f32_16x16x32_bf16 v[118:121], v[98:101], v[136:139], v[118:121]
	v_mfma_f32_16x16x32_bf16 v[122:125], v[102:105], v[132:135], 0
	v_mfma_f32_16x16x32_bf16 v[94:97], v[98:101], v[152:155], v[94:97]
	v_mfma_f32_16x16x32_bf16 v[98:101], v[102:105], v[140:143], 0
	v_mfma_f32_16x16x32_bf16 v[122:125], v[106:109], v[136:139], v[122:125]
	v_mfma_f32_16x16x32_bf16 v[98:101], v[106:109], v[152:155], v[98:101]
	s_nop 0
	s_barrier
	ds_read_b128 v[102:105], v145
	ds_read_b128 v[106:109], v145 offset:1024
	ds_read_b128 v[132:135], v145 offset:2048
	ds_read_b128 v[136:139], v145 offset:3072
	s_mov_b32 m0, s40
	v_lshl_add_u64 v[126:127], s[10:11], 0, v[0:1]
	ds_read_b128 v[140:143], v183 offset:32768
	ds_read_b128 v[152:155], v183 offset:33792
	ds_read_b128 v[184:187], v183 offset:34816
	ds_read_b128 v[188:191], v183 offset:35840
	ds_read_b128 v[192:195], v183 offset:36864
	ds_read_b128 v[196:199], v183 offset:37888
	ds_read_b128 v[200:203], v183 offset:38912
	ds_read_b128 v[204:207], v183 offset:39936
	global_load_lds_dwordx4 v[126:127], off
	v_lshl_add_u64 v[126:127], s[10:11], 0, v[2:3]
	s_mov_b32 m0, s18
	s_nop 0
	global_load_lds_dwordx4 v[126:127], off
	s_waitcnt lgkmcnt(8)
	s_barrier
	s_waitcnt lgkmcnt(0)
	s_nop 0
	s_waitcnt lgkmcnt(0)
	v_mfma_f32_16x16x32_bf16 v[62:65], v[102:105], v[140:143], v[62:65]
	v_mfma_f32_16x16x32_bf16 v[66:69], v[132:135], v[140:143], v[66:69]
	v_mfma_f32_16x16x32_bf16 v[70:73], v[102:105], v[184:187], v[70:73]
	v_mfma_f32_16x16x32_bf16 v[74:77], v[132:135], v[184:187], v[74:77]
	v_mfma_f32_16x16x32_bf16 v[78:81], v[102:105], v[192:195], v[78:81]
	v_mfma_f32_16x16x32_bf16 v[82:85], v[132:135], v[192:195], v[82:85]
	v_mfma_f32_16x16x32_bf16 v[86:89], v[102:105], v[200:203], v[86:89]
	v_mfma_f32_16x16x32_bf16 v[90:93], v[132:135], v[200:203], v[90:93]
	v_mfma_f32_16x16x32_bf16 v[62:65], v[106:109], v[152:155], v[62:65]
	v_mfma_f32_16x16x32_bf16 v[66:69], v[136:139], v[152:155], v[66:69]
	v_mfma_f32_16x16x32_bf16 v[70:73], v[106:109], v[188:191], v[70:73]
	v_mfma_f32_16x16x32_bf16 v[74:77], v[136:139], v[188:191], v[74:77]
	v_mfma_f32_16x16x32_bf16 v[78:81], v[106:109], v[196:199], v[78:81]
	v_mfma_f32_16x16x32_bf16 v[82:85], v[136:139], v[196:199], v[82:85]
	v_mfma_f32_16x16x32_bf16 v[86:89], v[106:109], v[204:207], v[86:89]
	v_mfma_f32_16x16x32_bf16 v[90:93], v[136:139], v[204:207], v[90:93]
	s_nop 0
	s_barrier
	s_mov_b32 m0, s36
	v_lshl_add_u64 v[12:13], v[12:13], 0, s[76:77]
	ds_read_b128 v[208:211], v146
	ds_read_b128 v[212:215], v146 offset:1024
	ds_read_b128 v[216:219], v146 offset:2048
	ds_read_b128 v[220:223], v146 offset:3072
	global_load_lds_dwordx4 v[12:13], off
	v_lshl_add_u64 v[10:11], v[10:11], 0, s[76:77]
	s_mov_b32 m0, s19
	s_nop 0
	global_load_lds_dwordx4 v[10:11], off
	s_barrier
	s_waitcnt lgkmcnt(0)
	s_nop 0
	s_waitcnt lgkmcnt(0)
	v_mfma_f32_16x16x32_bf16 v[10:13], v[208:211], v[140:143], v[110:113]
	v_mfma_f32_16x16x32_bf16 v[30:33], v[216:219], v[140:143], v[30:33]
	v_mfma_f32_16x16x32_bf16 v[34:37], v[208:211], v[184:187], v[34:37]
	v_mfma_f32_16x16x32_bf16 v[38:41], v[216:219], v[184:187], v[38:41]
	v_mfma_f32_16x16x32_bf16 v[42:45], v[208:211], v[192:195], v[42:45]
	v_mfma_f32_16x16x32_bf16 v[46:49], v[216:219], v[192:195], v[46:49]
	v_mfma_f32_16x16x32_bf16 v[50:53], v[208:211], v[200:203], v[50:53]
	v_mfma_f32_16x16x32_bf16 v[54:57], v[216:219], v[200:203], v[54:57]
	v_mfma_f32_16x16x32_bf16 v[10:13], v[212:215], v[152:155], v[10:13]
	v_mfma_f32_16x16x32_bf16 v[30:33], v[220:223], v[152:155], v[30:33]
	v_mfma_f32_16x16x32_bf16 v[34:37], v[212:215], v[188:191], v[34:37]
	v_mfma_f32_16x16x32_bf16 v[38:41], v[220:223], v[188:191], v[38:41]
	v_mfma_f32_16x16x32_bf16 v[42:45], v[212:215], v[196:199], v[42:45]
	v_mfma_f32_16x16x32_bf16 v[46:49], v[220:223], v[196:199], v[46:49]
	v_mfma_f32_16x16x32_bf16 v[50:53], v[212:215], v[204:207], v[50:53]
	v_mfma_f32_16x16x32_bf16 v[54:57], v[220:223], v[204:207], v[54:57]
	s_nop 0
	s_mov_b32 m0, s16
	v_lshl_add_u64 v[6:7], v[6:7], 0, s[76:77]
	s_barrier
	ds_read_b128 v[110:113], v183 offset:49152
	ds_read_b128 v[140:143], v183 offset:50176
	ds_read_b128 v[152:155], v183 offset:51200
	ds_read_b128 v[184:187], v183 offset:52224
	ds_read_b128 v[188:191], v183 offset:53248
	ds_read_b128 v[192:195], v183 offset:54272
	ds_read_b128 v[196:199], v183 offset:55296
	ds_read_b128 v[200:203], v183 offset:56320
	global_load_lds_dwordx4 v[6:7], off
	v_lshl_add_u64 v[6:7], v[8:9], 0, s[76:77]
	s_mov_b32 m0, s15
	s_nop 0
	global_load_lds_dwordx4 v[6:7], off
	s_barrier
	s_waitcnt lgkmcnt(0)
	s_nop 0
	s_waitcnt lgkmcnt(0)
	v_mfma_f32_16x16x32_bf16 v[6:9], v[102:105], v[110:113], v[156:159]
	v_mfma_f32_16x16x32_bf16 v[14:17], v[102:105], v[196:199], v[14:17]
	v_mfma_f32_16x16x32_bf16 v[18:21], v[132:135], v[196:199], v[18:21]
	v_mfma_f32_16x16x32_bf16 v[6:9], v[106:109], v[140:143], v[6:9]
	v_mfma_f32_16x16x32_bf16 v[156:159], v[132:135], v[110:113], v[160:163]
	v_mfma_f32_16x16x32_bf16 v[160:163], v[102:105], v[152:155], v[164:167]
	v_mfma_f32_16x16x32_bf16 v[164:167], v[132:135], v[152:155], v[168:171]
	v_mfma_f32_16x16x32_bf16 v[168:171], v[102:105], v[188:191], v[172:175]
	v_mfma_f32_16x16x32_bf16 v[172:175], v[132:135], v[188:191], v[176:179]
	v_mfma_f32_16x16x32_bf16 v[14:17], v[106:109], v[200:203], v[14:17]
	v_mfma_f32_16x16x32_bf16 v[18:21], v[136:139], v[200:203], v[18:21]
	v_mfma_f32_16x16x32_bf16 v[156:159], v[136:139], v[140:143], v[156:159]
	v_mfma_f32_16x16x32_bf16 v[160:163], v[106:109], v[184:187], v[160:163]
	v_mfma_f32_16x16x32_bf16 v[164:167], v[136:139], v[184:187], v[164:167]
	v_mfma_f32_16x16x32_bf16 v[168:171], v[106:109], v[192:195], v[168:171]
	v_mfma_f32_16x16x32_bf16 v[172:175], v[136:139], v[192:195], v[172:175]
	s_nop 0
	s_barrier
	s_mov_b32 m0, s2
	v_lshl_add_u64 v[102:103], s[6:7], 0, v[128:129]
	global_load_lds_dwordx4 v[102:103], off
	v_lshl_add_u64 v[4:5], s[6:7], 0, v[4:5]
	s_mov_b32 m0, s3
	s_nop 0
	global_load_lds_dwordx4 v[4:5], off
	s_waitcnt vmcnt(6)
	s_barrier
	s_nop 0
	v_mfma_f32_16x16x32_bf16 v[22:25], v[208:211], v[110:113], v[22:25]
	v_mfma_f32_16x16x32_bf16 v[26:29], v[216:219], v[110:113], v[26:29]
	v_mfma_f32_16x16x32_bf16 v[58:61], v[208:211], v[152:155], v[58:61]
	v_mfma_f32_16x16x32_bf16 v[102:105], v[216:219], v[152:155], v[114:117]
	v_mfma_f32_16x16x32_bf16 v[106:109], v[208:211], v[188:191], v[118:121]
	v_mfma_f32_16x16x32_bf16 v[110:113], v[216:219], v[188:191], v[122:125]
	v_mfma_f32_16x16x32_bf16 v[94:97], v[208:211], v[196:199], v[94:97]
	v_mfma_f32_16x16x32_bf16 v[98:101], v[216:219], v[196:199], v[98:101]
	v_mfma_f32_16x16x32_bf16 v[22:25], v[212:215], v[140:143], v[22:25]
	v_mfma_f32_16x16x32_bf16 v[26:29], v[220:223], v[140:143], v[26:29]
	v_mfma_f32_16x16x32_bf16 v[58:61], v[212:215], v[184:187], v[58:61]
	v_mfma_f32_16x16x32_bf16 v[102:105], v[220:223], v[184:187], v[102:105]
	v_mfma_f32_16x16x32_bf16 v[106:109], v[212:215], v[192:195], v[106:109]
	v_mfma_f32_16x16x32_bf16 v[110:113], v[220:223], v[192:195], v[110:113]
	v_mfma_f32_16x16x32_bf16 v[94:97], v[212:215], v[200:203], v[94:97]
	v_mfma_f32_16x16x32_bf16 v[98:101], v[220:223], v[200:203], v[98:101]
	s_nop 0
	s_add_u32 s2, s8, 0x10180
	s_addc_u32 s3, s9, 0
	s_mov_b32 m0, s17
	v_lshl_add_u64 v[0:1], s[2:3], 0, v[0:1]
	s_barrier
	ds_read_b128 v[114:117], v131
	ds_read_b128 v[118:121], v131 offset:1024
	ds_read_b128 v[122:125], v131 offset:2048
	ds_read_b128 v[132:135], v131 offset:3072
	ds_read_b128 v[136:139], v183
	ds_read_b128 v[140:143], v183 offset:1024
	ds_read_b128 v[152:155], v183 offset:2048
	ds_read_b128 v[176:179], v183 offset:3072
	ds_read_b128 v[184:187], v183 offset:4096
	ds_read_b128 v[188:191], v183 offset:5120
	ds_read_b128 v[192:195], v183 offset:6144
	ds_read_b128 v[196:199], v183 offset:7168
	global_load_lds_dwordx4 v[0:1], off
	v_lshl_add_u64 v[0:1], s[2:3], 0, v[2:3]
	s_mov_b32 m0, s14
	s_nop 0
	global_load_lds_dwordx4 v[0:1], off
	s_barrier
	s_waitcnt lgkmcnt(0)
	s_nop 0
	s_waitcnt lgkmcnt(0)
	v_mfma_f32_16x16x32_bf16 v[0:3], v[114:117], v[136:139], v[62:65]
	v_mfma_f32_16x16x32_bf16 v[62:65], v[122:125], v[136:139], v[66:69]
	v_mfma_f32_16x16x32_bf16 v[66:69], v[114:117], v[152:155], v[70:73]
	v_mfma_f32_16x16x32_bf16 v[70:73], v[122:125], v[152:155], v[74:77]
	v_mfma_f32_16x16x32_bf16 v[74:77], v[114:117], v[184:187], v[78:81]
	v_mfma_f32_16x16x32_bf16 v[78:81], v[122:125], v[184:187], v[82:85]
	v_mfma_f32_16x16x32_bf16 v[82:85], v[114:117], v[192:195], v[86:89]
	v_mfma_f32_16x16x32_bf16 v[0:3], v[118:121], v[140:143], v[0:3]
	v_mfma_f32_16x16x32_bf16 v[62:65], v[132:135], v[140:143], v[62:65]
	v_mfma_f32_16x16x32_bf16 v[66:69], v[118:121], v[176:179], v[66:69]
	v_mfma_f32_16x16x32_bf16 v[70:73], v[132:135], v[176:179], v[70:73]
	v_mfma_f32_16x16x32_bf16 v[74:77], v[118:121], v[188:191], v[74:77]
	v_mfma_f32_16x16x32_bf16 v[78:81], v[132:135], v[188:191], v[78:81]
	v_mfma_f32_16x16x32_bf16 v[82:85], v[118:121], v[196:199], v[82:85]
	v_mfma_f32_16x16x32_bf16 v[86:89], v[122:125], v[192:195], v[90:93]
	v_mfma_f32_16x16x32_bf16 v[200:203], v[132:135], v[196:199], v[86:89]
	s_nop 0
	s_barrier
	s_nop 4
	ds_read_b128 v[86:89], v144
	ds_read_b128 v[90:93], v144 offset:1024
	ds_read_b128 v[204:207], v144 offset:2048
	ds_read_b128 v[208:211], v144 offset:3072
	s_barrier
	s_waitcnt lgkmcnt(0)
	s_nop 0
	s_waitcnt lgkmcnt(0)
	v_mfma_f32_16x16x32_bf16 v[30:33], v[204:207], v[136:139], v[30:33]
	v_mfma_f32_16x16x32_bf16 v[10:13], v[86:89], v[136:139], v[10:13]
	v_mfma_f32_16x16x32_bf16 v[136:139], v[208:211], v[140:143], v[30:33]
	v_mfma_f32_16x16x32_bf16 v[30:33], v[86:89], v[152:155], v[34:37]
	v_mfma_f32_16x16x32_bf16 v[10:13], v[90:93], v[140:143], v[10:13]
	v_mfma_f32_16x16x32_bf16 v[140:143], v[90:93], v[176:179], v[30:33]
	v_mfma_f32_16x16x32_bf16 v[30:33], v[204:207], v[152:155], v[38:41]
	v_mfma_f32_16x16x32_bf16 v[152:155], v[208:211], v[176:179], v[30:33]
	v_mfma_f32_16x16x32_bf16 v[30:33], v[86:89], v[184:187], v[42:45]
	v_mfma_f32_16x16x32_bf16 v[40:43], v[90:93], v[188:191], v[30:33]
	v_mfma_f32_16x16x32_bf16 v[30:33], v[204:207], v[184:187], v[46:49]
	v_mfma_f32_16x16x32_bf16 v[44:47], v[208:211], v[188:191], v[30:33]
	v_mfma_f32_16x16x32_bf16 v[30:33], v[86:89], v[192:195], v[50:53]
	v_mfma_f32_16x16x32_bf16 v[48:51], v[90:93], v[196:199], v[30:33]
	v_mfma_f32_16x16x32_bf16 v[30:33], v[204:207], v[192:195], v[54:57]
	v_mfma_f32_16x16x32_bf16 v[52:55], v[208:211], v[196:199], v[30:33]
	s_nop 0
	s_barrier
	s_nop 4
	ds_read_b128 v[30:33], v183 offset:16384
	ds_read_b128 v[34:37], v183 offset:17408
	ds_read_b128 v[176:179], v183 offset:18432
	ds_read_b128 v[184:187], v183 offset:19456
	ds_read_b128 v[188:191], v183 offset:20480
	ds_read_b128 v[192:195], v183 offset:21504
	ds_read_b128 v[196:199], v183 offset:22528
	ds_read_b128 v[212:215], v183 offset:23552
	s_waitcnt vmcnt(4)
	s_barrier
	s_waitcnt lgkmcnt(0)
	s_nop 0
	s_waitcnt lgkmcnt(0)
	v_mfma_f32_16x16x32_bf16 v[4:7], v[114:117], v[30:33], v[6:9]
	v_mfma_f32_16x16x32_bf16 v[14:17], v[114:117], v[196:199], v[14:17]
	v_mfma_f32_16x16x32_bf16 v[4:7], v[118:121], v[34:37], v[4:7]
	v_mfma_f32_16x16x32_bf16 v[156:159], v[122:125], v[30:33], v[156:159]
	v_mfma_f32_16x16x32_bf16 v[160:163], v[114:117], v[176:179], v[160:163]
	v_mfma_f32_16x16x32_bf16 v[164:167], v[122:125], v[176:179], v[164:167]
	v_mfma_f32_16x16x32_bf16 v[168:171], v[114:117], v[188:191], v[168:171]
	v_mfma_f32_16x16x32_bf16 v[172:175], v[122:125], v[188:191], v[172:175]
	v_mfma_f32_16x16x32_bf16 v[216:219], v[118:121], v[212:215], v[14:17]
	v_mfma_f32_16x16x32_bf16 v[14:17], v[122:125], v[196:199], v[18:21]
	v_mfma_f32_16x16x32_bf16 v[156:159], v[132:135], v[34:37], v[156:159]
	v_mfma_f32_16x16x32_bf16 v[160:163], v[118:121], v[184:187], v[160:163]
	v_mfma_f32_16x16x32_bf16 v[164:167], v[132:135], v[184:187], v[164:167]
	v_mfma_f32_16x16x32_bf16 v[168:171], v[118:121], v[192:195], v[168:171]
	v_mfma_f32_16x16x32_bf16 v[172:175], v[132:135], v[192:195], v[172:175]
	v_mfma_f32_16x16x32_bf16 v[132:135], v[132:135], v[212:215], v[14:17]
	s_nop 0
	s_nop 0
	v_mfma_f32_16x16x32_bf16 v[14:17], v[86:89], v[30:33], v[22:25]
	v_mfma_f32_16x16x32_bf16 v[220:223], v[90:93], v[34:37], v[14:17]
	v_mfma_f32_16x16x32_bf16 v[14:17], v[204:207], v[30:33], v[26:29]
	v_mfma_f32_16x16x32_bf16 v[24:27], v[208:211], v[34:37], v[14:17]
	v_mfma_f32_16x16x32_bf16 v[14:17], v[86:89], v[176:179], v[58:61]
	v_mfma_f32_16x16x32_bf16 v[28:31], v[90:93], v[184:187], v[14:17]
	v_mfma_f32_16x16x32_bf16 v[14:17], v[204:207], v[176:179], v[102:105]
	v_mfma_f32_16x16x32_bf16 v[176:179], v[208:211], v[184:187], v[14:17]
	v_mfma_f32_16x16x32_bf16 v[14:17], v[86:89], v[188:191], v[106:109]
	v_mfma_f32_16x16x32_bf16 v[184:187], v[90:93], v[192:195], v[14:17]
	v_mfma_f32_16x16x32_bf16 v[14:17], v[204:207], v[188:191], v[110:113]
	v_mfma_f32_16x16x32_bf16 v[188:191], v[208:211], v[192:195], v[14:17]
	v_mfma_f32_16x16x32_bf16 v[14:17], v[86:89], v[196:199], v[94:97]
	v_mfma_f32_16x16x32_bf16 v[192:195], v[90:93], v[212:215], v[14:17]
	v_mfma_f32_16x16x32_bf16 v[14:17], v[204:207], v[196:199], v[98:101]
	v_mfma_f32_16x16x32_bf16 v[196:199], v[208:211], v[212:215], v[14:17]
	s_nop 0
	s_barrier
	ds_read_b128 v[204:207], v145
	ds_read_b128 v[208:211], v145 offset:1024
	ds_read_b128 v[212:215], v145 offset:2048
	ds_read_b128 v[224:227], v145 offset:3072
	s_nop 0
	ds_read_b128 v[14:17], v183 offset:32768
	ds_read_b128 v[18:21], v183 offset:33792
	ds_read_b128 v[96:99], v183 offset:34816
	ds_read_b128 v[100:103], v183 offset:35840
	ds_read_b128 v[228:231], v183 offset:36864
	ds_read_b128 v[232:235], v183 offset:37888
	ds_read_b128 v[236:239], v183 offset:38912
	ds_read_b128 v[240:243], v183 offset:39936
	s_waitcnt vmcnt(2)
	s_barrier
	s_waitcnt lgkmcnt(0)
	s_nop 0
	s_waitcnt lgkmcnt(0)
	v_mfma_f32_16x16x32_bf16 v[0:3], v[204:207], v[14:17], v[0:3]
	v_mfma_f32_16x16x32_bf16 v[104:107], v[208:211], v[18:21], v[0:3]
	v_mfma_f32_16x16x32_bf16 v[0:3], v[212:215], v[14:17], v[62:65]
	v_mfma_f32_16x16x32_bf16 v[108:111], v[224:227], v[18:21], v[0:3]
	v_mfma_f32_16x16x32_bf16 v[0:3], v[204:207], v[96:99], v[66:69]
	v_mfma_f32_16x16x32_bf16 v[88:91], v[208:211], v[100:103], v[0:3]
	v_mfma_f32_16x16x32_bf16 v[0:3], v[212:215], v[96:99], v[70:73]
	v_mfma_f32_16x16x32_bf16 v[92:95], v[224:227], v[100:103], v[0:3]
	v_mfma_f32_16x16x32_bf16 v[0:3], v[204:207], v[228:231], v[74:77]
	v_mfma_f32_16x16x32_bf16 v[56:59], v[208:211], v[232:235], v[0:3]
	v_mfma_f32_16x16x32_bf16 v[0:3], v[212:215], v[228:231], v[78:81]
	v_mfma_f32_16x16x32_bf16 v[60:63], v[224:227], v[232:235], v[0:3]
	v_mfma_f32_16x16x32_bf16 v[0:3], v[204:207], v[236:239], v[82:85]
	v_mfma_f32_16x16x32_bf16 v[32:35], v[208:211], v[240:243], v[0:3]
	v_mfma_f32_16x16x32_bf16 v[0:3], v[212:215], v[236:239], v[200:203]
	v_mfma_f32_16x16x32_bf16 v[36:39], v[224:227], v[240:243], v[0:3]
	s_nop 0
	s_barrier
	ds_read_b128 v[200:203], v146
	ds_read_b128 v[244:247], v146 offset:1024
	ds_read_b128 v[248:251], v146 offset:2048
	ds_read_b128 v[144:147], v146 offset:3072
	s_waitcnt vmcnt(0)
	s_barrier
	s_waitcnt lgkmcnt(0)
	s_nop 0
	s_waitcnt lgkmcnt(0)
	v_mfma_f32_16x16x32_bf16 v[0:3], v[200:203], v[14:17], v[10:13]
	v_mfma_f32_16x16x32_bf16 v[120:123], v[244:247], v[18:21], v[0:3]
	v_mfma_f32_16x16x32_bf16 v[0:3], v[248:251], v[14:17], v[136:139]
	v_mfma_f32_16x16x32_bf16 v[124:127], v[144:147], v[18:21], v[0:3]
	v_mfma_f32_16x16x32_bf16 v[0:3], v[200:203], v[96:99], v[140:143]
	v_mfma_f32_16x16x32_bf16 v[112:115], v[244:247], v[100:103], v[0:3]
	v_mfma_f32_16x16x32_bf16 v[0:3], v[248:251], v[96:99], v[152:155]
	v_mfma_f32_16x16x32_bf16 v[116:119], v[144:147], v[100:103], v[0:3]
	v_mfma_f32_16x16x32_bf16 v[0:3], v[200:203], v[228:231], v[40:43]
	v_mfma_f32_16x16x32_bf16 v[96:99], v[244:247], v[232:235], v[0:3]
	v_mfma_f32_16x16x32_bf16 v[0:3], v[248:251], v[228:231], v[44:47]
	v_mfma_f32_16x16x32_bf16 v[100:103], v[144:147], v[232:235], v[0:3]
	v_mfma_f32_16x16x32_bf16 v[0:3], v[200:203], v[236:239], v[48:51]
	v_mfma_f32_16x16x32_bf16 v[64:67], v[244:247], v[240:243], v[0:3]
	v_mfma_f32_16x16x32_bf16 v[0:3], v[248:251], v[236:239], v[52:55]
	v_mfma_f32_16x16x32_bf16 v[68:71], v[144:147], v[240:243], v[0:3]
	s_nop 0
	s_barrier
	ds_read_b128 v[8:11], v183 offset:49152
	ds_read_b128 v[12:15], v183 offset:50176
	ds_read_b128 v[52:55], v183 offset:51200
	ds_read_b128 v[136:139], v183 offset:52224
	ds_read_b128 v[140:143], v183 offset:53248
	ds_read_b128 v[152:155], v183 offset:54272
	ds_read_b128 v[228:231], v183 offset:55296
	ds_read_b128 v[232:235], v183 offset:56320
	s_barrier
	s_waitcnt lgkmcnt(0)
	s_nop 0
	s_waitcnt lgkmcnt(0)
	v_mfma_f32_16x16x32_bf16 v[0:3], v[204:207], v[8:11], v[4:7]
	v_mfma_f32_16x16x32_bf16 v[72:75], v[208:211], v[12:15], v[0:3]
	v_mfma_f32_16x16x32_bf16 v[0:3], v[212:215], v[8:11], v[156:159]
	v_mfma_f32_16x16x32_bf16 v[76:79], v[224:227], v[12:15], v[0:3]
	v_mfma_f32_16x16x32_bf16 v[0:3], v[204:207], v[52:55], v[160:163]
	v_mfma_f32_16x16x32_bf16 v[40:43], v[208:211], v[136:139], v[0:3]
	v_mfma_f32_16x16x32_bf16 v[0:3], v[212:215], v[52:55], v[164:167]
	v_mfma_f32_16x16x32_bf16 v[44:47], v[224:227], v[136:139], v[0:3]
	v_mfma_f32_16x16x32_bf16 v[0:3], v[204:207], v[140:143], v[168:171]
	v_mfma_f32_16x16x32_bf16 v[16:19], v[208:211], v[152:155], v[0:3]
	v_mfma_f32_16x16x32_bf16 v[0:3], v[212:215], v[140:143], v[172:175]
	v_mfma_f32_16x16x32_bf16 v[20:23], v[224:227], v[152:155], v[0:3]
	v_mfma_f32_16x16x32_bf16 v[0:3], v[204:207], v[228:231], v[216:219]
	v_mfma_f32_16x16x32_bf16 v[4:7], v[212:215], v[228:231], v[132:135]
	v_mfma_f32_16x16x32_bf16 v[0:3], v[208:211], v[232:235], v[0:3]
	v_mfma_f32_16x16x32_bf16 v[4:7], v[224:227], v[232:235], v[4:7]
	s_nop 0
	s_nop 0
	v_mfma_f32_16x16x32_bf16 v[48:51], v[200:203], v[8:11], v[220:223]
	v_mfma_f32_16x16x32_bf16 v[8:11], v[248:251], v[8:11], v[24:27]
	v_mfma_f32_16x16x32_bf16 v[84:87], v[144:147], v[12:15], v[8:11]
	v_mfma_f32_16x16x32_bf16 v[8:11], v[200:203], v[52:55], v[28:31]
	v_mfma_f32_16x16x32_bf16 v[80:83], v[244:247], v[12:15], v[48:51]
	v_mfma_f32_16x16x32_bf16 v[48:51], v[244:247], v[136:139], v[8:11]
	v_mfma_f32_16x16x32_bf16 v[8:11], v[248:251], v[52:55], v[176:179]
	v_mfma_f32_16x16x32_bf16 v[52:55], v[144:147], v[136:139], v[8:11]
	v_mfma_f32_16x16x32_bf16 v[8:11], v[200:203], v[140:143], v[184:187]
	v_mfma_f32_16x16x32_bf16 v[24:27], v[244:247], v[152:155], v[8:11]
	v_mfma_f32_16x16x32_bf16 v[8:11], v[248:251], v[140:143], v[188:191]
	v_mfma_f32_16x16x32_bf16 v[28:31], v[144:147], v[152:155], v[8:11]
	v_mfma_f32_16x16x32_bf16 v[8:11], v[200:203], v[228:231], v[192:195]
	v_mfma_f32_16x16x32_bf16 v[12:15], v[248:251], v[228:231], v[196:199]
	v_mfma_f32_16x16x32_bf16 v[8:11], v[244:247], v[232:235], v[8:11]
	v_mfma_f32_16x16x32_bf16 v[12:15], v[144:147], v[232:235], v[12:15]
	s_nop 0
	s_cmpk_gt_u32 s0, 0xff
	s_barrier
	s_cbranch_scc1 .LBB0_261
	s_barrier
	s_branch .LBB0_261

.LBB0_637:
	s_add_i32 s83, s74, s80
	s_lshl_b32 s27, s27, 12
	v_lshl_add_u64 v[16:17], v[12:13], 0, s[10:11]
	s_mov_b32 m0, s83
	s_add_i32 s79, s83, 0x2000
	s_lshl_b32 s28, s26, 13
	s_and_b32 s29, s27, 0x3000
	s_waitcnt vmcnt(4)
	s_barrier
	global_load_lds_dwordx4 v[16:17], off
	v_lshl_add_u64 v[16:17], v[10:11], 0, s[10:11]
	s_mov_b32 m0, s79
	s_add_i32 s49, s85, 0x8000
	s_add_i32 s48, s85, 0xa000
	global_load_lds_dwordx4 v[16:17], off
	v_lshl_add_u64 v[16:17], v[6:7], 0, s[10:11]
	s_mov_b32 m0, s49
	s_add_u32 s26, s22, 0x40080
	global_load_lds_dwordx4 v[16:17], off
	v_lshl_add_u64 v[16:17], v[8:9], 0, s[10:11]
	s_mov_b32 m0, s48
	s_addc_u32 s27, s23, 0
	s_add_i32 s30, s75, s80
	global_load_lds_dwordx4 v[16:17], off
	v_lshl_add_u64 v[16:17], s[26:27], 0, v[152:153]
	s_mov_b32 m0, s30
	s_add_i32 s31, s30, 0x2000
	global_load_lds_dwordx4 v[16:17], off
	v_lshl_add_u64 v[16:17], s[26:27], 0, v[4:5]
	s_mov_b32 m0, s31
	v_and_b32_e32 v15, 15, v14
	global_load_lds_dwordx4 v[16:17], off
	v_and_b32_e32 v16, 48, v14
	v_lshlrev_b32_e32 v14, 2, v14
	v_lshlrev_b32_e32 v15, 6, v15
	v_and_b32_e32 v14, 32, v14
	v_or_b32_e32 v17, v15, v16
	v_bitop3_b32 v15, v15, v14, v16 bitop3:0x36
	v_or_b32_e32 v64, s29, v15
	s_add_i32 s82, 0, 0x10000
	v_bitop3_b32 v14, v17, s28, v14 bitop3:0xde
	v_add_u32_e32 v185, s82, v64
	s_waitcnt vmcnt(6)
	s_barrier
	s_add_u32 s60, s0, 0x40080
	v_add_u32_e32 v238, 0, v14
	ds_read_b128 v[14:17], v185
	ds_read_b128 v[18:21], v185 offset:1024
	ds_read_b128 v[22:25], v185 offset:2048
	ds_read_b128 v[26:29], v185 offset:3072
	s_addc_u32 s61, s1, 0
	s_add_i32 s43, 0, 0x14000
	s_add_u32 s28, s22, 0x40100
	s_addc_u32 s29, s23, 0
	s_add_u32 s26, s0, 0x40100
	s_addc_u32 s27, s1, 0
	s_add_u32 s22, s22, 0x40180
	v_add_u32_e32 v214, s43, v64
	s_addc_u32 s23, s23, 0
	s_add_i32 s50, s85, 0xc000
	v_lshl_add_u64 v[62:63], s[60:61], 0, v[0:1]
	s_mov_b32 m0, s50
	s_add_i32 s42, s85, 0xe000
	ds_read_b128 v[30:33], v238
	ds_read_b128 v[34:37], v238 offset:1024
	ds_read_b128 v[38:41], v238 offset:2048
	ds_read_b128 v[42:45], v238 offset:3072
	ds_read_b128 v[46:49], v238 offset:4096
	ds_read_b128 v[50:53], v238 offset:5120
	ds_read_b128 v[54:57], v238 offset:6144
	ds_read_b128 v[58:61], v238 offset:7168
	global_load_lds_dwordx4 v[62:63], off
	v_lshl_add_u64 v[62:63], s[60:61], 0, v[2:3]
	s_mov_b32 m0, s42
	v_add_u32_e32 v215, s74, v64
	global_load_lds_dwordx4 v[62:63], off
	s_waitcnt lgkmcnt(8)
	s_barrier
	s_waitcnt lgkmcnt(0)
	v_add_u32_e32 v230, s75, v64
	s_nop 0
	s_waitcnt lgkmcnt(0)
	v_mfma_f32_16x16x32_bf16 v[62:65], v[14:17], v[30:33], 0
	v_mfma_f32_16x16x32_bf16 v[66:69], v[22:25], v[30:33], 0
	v_mfma_f32_16x16x32_bf16 v[70:73], v[14:17], v[38:41], 0
	v_mfma_f32_16x16x32_bf16 v[74:77], v[22:25], v[38:41], 0
	v_mfma_f32_16x16x32_bf16 v[78:81], v[14:17], v[46:49], 0
	v_mfma_f32_16x16x32_bf16 v[82:85], v[22:25], v[46:49], 0
	v_mfma_f32_16x16x32_bf16 v[86:89], v[14:17], v[54:57], 0
	v_mfma_f32_16x16x32_bf16 v[90:93], v[22:25], v[54:57], 0
	v_mfma_f32_16x16x32_bf16 v[62:65], v[18:21], v[34:37], v[62:65]
	v_mfma_f32_16x16x32_bf16 v[66:69], v[26:29], v[34:37], v[66:69]
	v_mfma_f32_16x16x32_bf16 v[70:73], v[18:21], v[42:45], v[70:73]
	v_mfma_f32_16x16x32_bf16 v[74:77], v[26:29], v[42:45], v[74:77]
	v_mfma_f32_16x16x32_bf16 v[78:81], v[18:21], v[50:53], v[78:81]
	v_mfma_f32_16x16x32_bf16 v[82:85], v[26:29], v[50:53], v[82:85]
	v_mfma_f32_16x16x32_bf16 v[86:89], v[18:21], v[58:61], v[86:89]
	v_mfma_f32_16x16x32_bf16 v[90:93], v[26:29], v[58:61], v[90:93]
	s_nop 0
	s_barrier
	s_add_i32 s60, s82, s80
	v_lshl_add_u64 v[110:111], v[12:13], 0, s[12:13]
	s_mov_b32 m0, s60
	ds_read_b128 v[94:97], v214
	ds_read_b128 v[98:101], v214 offset:1024
	ds_read_b128 v[102:105], v214 offset:2048
	ds_read_b128 v[106:109], v214 offset:3072
	global_load_lds_dwordx4 v[110:111], off
	v_lshl_add_u64 v[110:111], v[10:11], 0, s[12:13]
	s_add_i32 m0, s60, 0x2000
	s_nop 0
	global_load_lds_dwordx4 v[110:111], off
	s_barrier
	s_waitcnt lgkmcnt(0)
	s_nop 0
	s_waitcnt lgkmcnt(0)
	v_mfma_f32_16x16x32_bf16 v[110:113], v[94:97], v[30:33], 0
	v_mfma_f32_16x16x32_bf16 v[30:33], v[102:105], v[30:33], 0
	v_mfma_f32_16x16x32_bf16 v[110:113], v[98:101], v[34:37], v[110:113]
	v_mfma_f32_16x16x32_bf16 v[30:33], v[106:109], v[34:37], v[30:33]
	v_mfma_f32_16x16x32_bf16 v[34:37], v[94:97], v[38:41], 0
	v_mfma_f32_16x16x32_bf16 v[38:41], v[102:105], v[38:41], 0
	v_mfma_f32_16x16x32_bf16 v[34:37], v[98:101], v[42:45], v[34:37]
	v_mfma_f32_16x16x32_bf16 v[38:41], v[106:109], v[42:45], v[38:41]
	v_mfma_f32_16x16x32_bf16 v[42:45], v[94:97], v[46:49], 0
	v_mfma_f32_16x16x32_bf16 v[46:49], v[102:105], v[46:49], 0
	v_mfma_f32_16x16x32_bf16 v[42:45], v[98:101], v[50:53], v[42:45]
	v_mfma_f32_16x16x32_bf16 v[46:49], v[106:109], v[50:53], v[46:49]
	v_mfma_f32_16x16x32_bf16 v[50:53], v[94:97], v[54:57], 0
	v_mfma_f32_16x16x32_bf16 v[54:57], v[102:105], v[54:57], 0
	v_mfma_f32_16x16x32_bf16 v[50:53], v[98:101], v[58:61], v[50:53]
	v_mfma_f32_16x16x32_bf16 v[54:57], v[106:109], v[58:61], v[54:57]
	s_nop 0
	s_mov_b32 m0, s85
	v_lshl_add_u64 v[142:143], v[6:7], 0, s[12:13]
	s_barrier
	ds_read_b128 v[58:61], v238 offset:16384
	ds_read_b128 v[114:117], v238 offset:17408
	ds_read_b128 v[118:121], v238 offset:18432
	ds_read_b128 v[122:125], v238 offset:19456
	ds_read_b128 v[126:129], v238 offset:20480
	ds_read_b128 v[130:133], v238 offset:21504
	ds_read_b128 v[134:137], v238 offset:22528
	ds_read_b128 v[138:141], v238 offset:23552
	global_load_lds_dwordx4 v[142:143], off
	v_lshl_add_u64 v[142:143], v[8:9], 0, s[12:13]
	s_mov_b32 m0, s86
	s_nop 0
	global_load_lds_dwordx4 v[142:143], off
	s_barrier
	s_waitcnt lgkmcnt(0)
	s_nop 0
	s_waitcnt lgkmcnt(0)
	v_mfma_f32_16x16x32_bf16 v[142:145], v[14:17], v[58:61], 0
	v_mfma_f32_16x16x32_bf16 v[154:157], v[14:17], v[118:121], 0
	v_mfma_f32_16x16x32_bf16 v[162:165], v[14:17], v[126:129], 0
	v_mfma_f32_16x16x32_bf16 v[14:17], v[14:17], v[134:137], 0
	v_mfma_f32_16x16x32_bf16 v[142:145], v[18:21], v[114:117], v[142:145]
	v_mfma_f32_16x16x32_bf16 v[154:157], v[18:21], v[122:125], v[154:157]
	v_mfma_f32_16x16x32_bf16 v[162:165], v[18:21], v[130:133], v[162:165]
	v_mfma_f32_16x16x32_bf16 v[14:17], v[18:21], v[138:141], v[14:17]
	v_mfma_f32_16x16x32_bf16 v[18:21], v[22:25], v[134:137], 0
	v_mfma_f32_16x16x32_bf16 v[146:149], v[22:25], v[58:61], 0
	v_mfma_f32_16x16x32_bf16 v[158:161], v[22:25], v[118:121], 0
	v_mfma_f32_16x16x32_bf16 v[166:169], v[22:25], v[126:129], 0
	v_mfma_f32_16x16x32_bf16 v[18:21], v[26:29], v[138:141], v[18:21]
	v_mfma_f32_16x16x32_bf16 v[146:149], v[26:29], v[114:117], v[146:149]
	v_mfma_f32_16x16x32_bf16 v[158:161], v[26:29], v[122:125], v[158:161]
	v_mfma_f32_16x16x32_bf16 v[166:169], v[26:29], v[130:133], v[166:169]
	s_nop 0
	s_barrier
	s_add_i32 s60, s43, s80
	v_lshl_add_u64 v[22:23], s[28:29], 0, v[152:153]
	s_mov_b32 m0, s60
	s_nop 0
	global_load_lds_dwordx4 v[22:23], off
	v_lshl_add_u64 v[22:23], s[28:29], 0, v[4:5]
	s_add_i32 m0, s60, 0x2000
	s_nop 0
	global_load_lds_dwordx4 v[22:23], off
	s_waitcnt vmcnt(6)
	s_barrier
	s_nop 0
	v_mfma_f32_16x16x32_bf16 v[22:25], v[94:97], v[58:61], 0
	v_mfma_f32_16x16x32_bf16 v[26:29], v[102:105], v[58:61], 0
	v_mfma_f32_16x16x32_bf16 v[22:25], v[98:101], v[114:117], v[22:25]
	v_mfma_f32_16x16x32_bf16 v[26:29], v[106:109], v[114:117], v[26:29]
	v_mfma_f32_16x16x32_bf16 v[58:61], v[94:97], v[118:121], 0
	v_mfma_f32_16x16x32_bf16 v[114:117], v[102:105], v[118:121], 0
	v_mfma_f32_16x16x32_bf16 v[118:121], v[94:97], v[126:129], 0
	v_mfma_f32_16x16x32_bf16 v[94:97], v[94:97], v[134:137], 0
	v_mfma_f32_16x16x32_bf16 v[58:61], v[98:101], v[122:125], v[58:61]
	v_mfma_f32_16x16x32_bf16 v[114:117], v[106:109], v[122:125], v[114:117]
	v_mfma_f32_16x16x32_bf16 v[118:121], v[98:101], v[130:133], v[118:121]
	v_mfma_f32_16x16x32_bf16 v[122:125], v[102:105], v[126:129], 0
	v_mfma_f32_16x16x32_bf16 v[94:97], v[98:101], v[138:141], v[94:97]
	v_mfma_f32_16x16x32_bf16 v[98:101], v[102:105], v[134:137], 0
	v_mfma_f32_16x16x32_bf16 v[122:125], v[106:109], v[130:133], v[122:125]
	v_mfma_f32_16x16x32_bf16 v[98:101], v[106:109], v[138:141], v[98:101]
	s_nop 0
	s_barrier
	ds_read_b128 v[102:105], v215
	ds_read_b128 v[106:109], v215 offset:1024
	ds_read_b128 v[126:129], v215 offset:2048
	ds_read_b128 v[130:133], v215 offset:3072
	s_mov_b32 m0, s84
	v_lshl_add_u64 v[150:151], s[26:27], 0, v[0:1]
	ds_read_b128 v[134:137], v238 offset:32768
	ds_read_b128 v[138:141], v238 offset:33792
	ds_read_b128 v[170:173], v238 offset:34816
	ds_read_b128 v[174:177], v238 offset:35840
	ds_read_b128 v[178:181], v238 offset:36864
	ds_read_b128 v[186:189], v238 offset:37888
	ds_read_b128 v[190:193], v238 offset:38912
	ds_read_b128 v[194:197], v238 offset:39936
	global_load_lds_dwordx4 v[150:151], off
	v_lshl_add_u64 v[150:151], s[26:27], 0, v[2:3]
	s_mov_b32 m0, s51
	s_nop 0
	global_load_lds_dwordx4 v[150:151], off
	s_waitcnt lgkmcnt(8)
	s_barrier
	s_waitcnt lgkmcnt(0)
	s_nop 0
	s_waitcnt lgkmcnt(0)
	v_mfma_f32_16x16x32_bf16 v[62:65], v[102:105], v[134:137], v[62:65]
	v_mfma_f32_16x16x32_bf16 v[66:69], v[126:129], v[134:137], v[66:69]
	v_mfma_f32_16x16x32_bf16 v[70:73], v[102:105], v[170:173], v[70:73]
	v_mfma_f32_16x16x32_bf16 v[74:77], v[126:129], v[170:173], v[74:77]
	v_mfma_f32_16x16x32_bf16 v[78:81], v[102:105], v[178:181], v[78:81]
	v_mfma_f32_16x16x32_bf16 v[82:85], v[126:129], v[178:181], v[82:85]
	v_mfma_f32_16x16x32_bf16 v[86:89], v[102:105], v[190:193], v[86:89]
	v_mfma_f32_16x16x32_bf16 v[90:93], v[126:129], v[190:193], v[90:93]
	v_mfma_f32_16x16x32_bf16 v[62:65], v[106:109], v[138:141], v[62:65]
	v_mfma_f32_16x16x32_bf16 v[66:69], v[130:133], v[138:141], v[66:69]
	v_mfma_f32_16x16x32_bf16 v[70:73], v[106:109], v[174:177], v[70:73]
	v_mfma_f32_16x16x32_bf16 v[74:77], v[130:133], v[174:177], v[74:77]
	v_mfma_f32_16x16x32_bf16 v[78:81], v[106:109], v[186:189], v[78:81]
	v_mfma_f32_16x16x32_bf16 v[82:85], v[130:133], v[186:189], v[82:85]
	v_mfma_f32_16x16x32_bf16 v[86:89], v[106:109], v[194:197], v[86:89]
	v_mfma_f32_16x16x32_bf16 v[90:93], v[130:133], v[194:197], v[90:93]
	s_nop 0
	s_barrier
	s_mov_b32 m0, s83
	v_lshl_add_u64 v[12:13], v[12:13], 0, s[14:15]
	ds_read_b128 v[198:201], v230
	ds_read_b128 v[202:205], v230 offset:1024
	ds_read_b128 v[206:209], v230 offset:2048
	ds_read_b128 v[210:213], v230 offset:3072
	global_load_lds_dwordx4 v[12:13], off
	v_lshl_add_u64 v[10:11], v[10:11], 0, s[14:15]
	s_mov_b32 m0, s79
	s_nop 0
	global_load_lds_dwordx4 v[10:11], off
	s_barrier
	s_waitcnt lgkmcnt(0)
	s_nop 0
	s_waitcnt lgkmcnt(0)
	v_mfma_f32_16x16x32_bf16 v[10:13], v[198:201], v[134:137], v[110:113]
	v_mfma_f32_16x16x32_bf16 v[30:33], v[206:209], v[134:137], v[30:33]
	v_mfma_f32_16x16x32_bf16 v[34:37], v[198:201], v[170:173], v[34:37]
	v_mfma_f32_16x16x32_bf16 v[38:41], v[206:209], v[170:173], v[38:41]
	v_mfma_f32_16x16x32_bf16 v[42:45], v[198:201], v[178:181], v[42:45]
	v_mfma_f32_16x16x32_bf16 v[46:49], v[206:209], v[178:181], v[46:49]
	v_mfma_f32_16x16x32_bf16 v[50:53], v[198:201], v[190:193], v[50:53]
	v_mfma_f32_16x16x32_bf16 v[54:57], v[206:209], v[190:193], v[54:57]
	v_mfma_f32_16x16x32_bf16 v[10:13], v[202:205], v[138:141], v[10:13]
	v_mfma_f32_16x16x32_bf16 v[30:33], v[210:213], v[138:141], v[30:33]
	v_mfma_f32_16x16x32_bf16 v[34:37], v[202:205], v[174:177], v[34:37]
	v_mfma_f32_16x16x32_bf16 v[38:41], v[210:213], v[174:177], v[38:41]
	v_mfma_f32_16x16x32_bf16 v[42:45], v[202:205], v[186:189], v[42:45]
	v_mfma_f32_16x16x32_bf16 v[46:49], v[210:213], v[186:189], v[46:49]
	v_mfma_f32_16x16x32_bf16 v[50:53], v[202:205], v[194:197], v[50:53]
	v_mfma_f32_16x16x32_bf16 v[54:57], v[210:213], v[194:197], v[54:57]
	s_nop 0
	s_mov_b32 m0, s49
	v_lshl_add_u64 v[6:7], v[6:7], 0, s[14:15]
	s_barrier
	ds_read_b128 v[110:113], v238 offset:49152
	ds_read_b128 v[134:137], v238 offset:50176
	ds_read_b128 v[138:141], v238 offset:51200
	ds_read_b128 v[170:173], v238 offset:52224
	ds_read_b128 v[174:177], v238 offset:53248
	ds_read_b128 v[178:181], v238 offset:54272
	ds_read_b128 v[186:189], v238 offset:55296
	ds_read_b128 v[190:193], v238 offset:56320
	global_load_lds_dwordx4 v[6:7], off
	v_lshl_add_u64 v[6:7], v[8:9], 0, s[14:15]
	s_mov_b32 m0, s48
	s_nop 0
	global_load_lds_dwordx4 v[6:7], off
	s_barrier
	s_waitcnt lgkmcnt(0)
	s_nop 0
	s_waitcnt lgkmcnt(0)
	v_mfma_f32_16x16x32_bf16 v[6:9], v[102:105], v[110:113], v[142:145]
	v_mfma_f32_16x16x32_bf16 v[14:17], v[102:105], v[186:189], v[14:17]
	v_mfma_f32_16x16x32_bf16 v[18:21], v[126:129], v[186:189], v[18:21]
	v_mfma_f32_16x16x32_bf16 v[6:9], v[106:109], v[134:137], v[6:9]
	v_mfma_f32_16x16x32_bf16 v[142:145], v[126:129], v[110:113], v[146:149]
	v_mfma_f32_16x16x32_bf16 v[146:149], v[102:105], v[138:141], v[154:157]
	v_mfma_f32_16x16x32_bf16 v[154:157], v[126:129], v[138:141], v[158:161]
	v_mfma_f32_16x16x32_bf16 v[158:161], v[102:105], v[174:177], v[162:165]
	v_mfma_f32_16x16x32_bf16 v[162:165], v[126:129], v[174:177], v[166:169]
	v_mfma_f32_16x16x32_bf16 v[14:17], v[106:109], v[190:193], v[14:17]
	v_mfma_f32_16x16x32_bf16 v[18:21], v[130:133], v[190:193], v[18:21]
	v_mfma_f32_16x16x32_bf16 v[142:145], v[130:133], v[134:137], v[142:145]
	v_mfma_f32_16x16x32_bf16 v[146:149], v[106:109], v[170:173], v[146:149]
	v_mfma_f32_16x16x32_bf16 v[154:157], v[130:133], v[170:173], v[154:157]
	v_mfma_f32_16x16x32_bf16 v[158:161], v[106:109], v[178:181], v[158:161]
	v_mfma_f32_16x16x32_bf16 v[162:165], v[130:133], v[178:181], v[162:165]
	s_nop 0
	s_barrier
	s_mov_b32 m0, s30
	v_lshl_add_u64 v[102:103], s[22:23], 0, v[152:153]
	global_load_lds_dwordx4 v[102:103], off
	v_lshl_add_u64 v[4:5], s[22:23], 0, v[4:5]
	s_mov_b32 m0, s31
	s_nop 0
	global_load_lds_dwordx4 v[4:5], off
	s_waitcnt vmcnt(6)
	s_barrier
	s_nop 0
	v_mfma_f32_16x16x32_bf16 v[22:25], v[198:201], v[110:113], v[22:25]
	v_mfma_f32_16x16x32_bf16 v[26:29], v[206:209], v[110:113], v[26:29]
	v_mfma_f32_16x16x32_bf16 v[58:61], v[198:201], v[138:141], v[58:61]
	v_mfma_f32_16x16x32_bf16 v[102:105], v[206:209], v[138:141], v[114:117]
	v_mfma_f32_16x16x32_bf16 v[106:109], v[198:201], v[174:177], v[118:121]
	v_mfma_f32_16x16x32_bf16 v[110:113], v[206:209], v[174:177], v[122:125]
	v_mfma_f32_16x16x32_bf16 v[94:97], v[198:201], v[186:189], v[94:97]
	v_mfma_f32_16x16x32_bf16 v[98:101], v[206:209], v[186:189], v[98:101]
	v_mfma_f32_16x16x32_bf16 v[22:25], v[202:205], v[134:137], v[22:25]
	v_mfma_f32_16x16x32_bf16 v[26:29], v[210:213], v[134:137], v[26:29]
	v_mfma_f32_16x16x32_bf16 v[58:61], v[202:205], v[170:173], v[58:61]
	v_mfma_f32_16x16x32_bf16 v[102:105], v[210:213], v[170:173], v[102:105]
	v_mfma_f32_16x16x32_bf16 v[106:109], v[202:205], v[178:181], v[106:109]
	v_mfma_f32_16x16x32_bf16 v[110:113], v[210:213], v[178:181], v[110:113]
	v_mfma_f32_16x16x32_bf16 v[94:97], v[202:205], v[190:193], v[94:97]
	v_mfma_f32_16x16x32_bf16 v[98:101], v[210:213], v[190:193], v[98:101]
	s_nop 0
	s_add_u32 s0, s0, 0x40180
	s_addc_u32 s1, s1, 0
	s_mov_b32 m0, s50
	v_lshl_add_u64 v[0:1], s[0:1], 0, v[0:1]
	s_barrier
	ds_read_b128 v[114:117], v185
	ds_read_b128 v[118:121], v185 offset:1024
	ds_read_b128 v[122:125], v185 offset:2048
	ds_read_b128 v[126:129], v185 offset:3072
	ds_read_b128 v[130:133], v238
	ds_read_b128 v[134:137], v238 offset:1024
	ds_read_b128 v[138:141], v238 offset:2048
	ds_read_b128 v[166:169], v238 offset:3072
	ds_read_b128 v[170:173], v238 offset:4096
	ds_read_b128 v[174:177], v238 offset:5120
	ds_read_b128 v[178:181], v238 offset:6144
	ds_read_b128 v[186:189], v238 offset:7168
	global_load_lds_dwordx4 v[0:1], off
	v_lshl_add_u64 v[0:1], s[0:1], 0, v[2:3]
	s_mov_b32 m0, s42
	s_nop 0
	global_load_lds_dwordx4 v[0:1], off
	s_barrier
	s_waitcnt lgkmcnt(0)
	s_nop 0
	s_waitcnt lgkmcnt(0)
	v_mfma_f32_16x16x32_bf16 v[0:3], v[114:117], v[130:133], v[62:65]
	v_mfma_f32_16x16x32_bf16 v[62:65], v[122:125], v[130:133], v[66:69]
	v_mfma_f32_16x16x32_bf16 v[66:69], v[114:117], v[138:141], v[70:73]
	v_mfma_f32_16x16x32_bf16 v[70:73], v[122:125], v[138:141], v[74:77]
	v_mfma_f32_16x16x32_bf16 v[74:77], v[114:117], v[170:173], v[78:81]
	v_mfma_f32_16x16x32_bf16 v[78:81], v[122:125], v[170:173], v[82:85]
	v_mfma_f32_16x16x32_bf16 v[82:85], v[114:117], v[178:181], v[86:89]
	v_mfma_f32_16x16x32_bf16 v[0:3], v[118:121], v[134:137], v[0:3]
	v_mfma_f32_16x16x32_bf16 v[62:65], v[126:129], v[134:137], v[62:65]
	v_mfma_f32_16x16x32_bf16 v[66:69], v[118:121], v[166:169], v[66:69]
	v_mfma_f32_16x16x32_bf16 v[70:73], v[126:129], v[166:169], v[70:73]
	v_mfma_f32_16x16x32_bf16 v[74:77], v[118:121], v[174:177], v[74:77]
	v_mfma_f32_16x16x32_bf16 v[78:81], v[126:129], v[174:177], v[78:81]
	v_mfma_f32_16x16x32_bf16 v[82:85], v[118:121], v[186:189], v[82:85]
	v_mfma_f32_16x16x32_bf16 v[86:89], v[122:125], v[178:181], v[90:93]
	v_mfma_f32_16x16x32_bf16 v[190:193], v[126:129], v[186:189], v[86:89]
	s_nop 0
	s_barrier
	s_nop 4
	ds_read_b128 v[86:89], v214
	ds_read_b128 v[90:93], v214 offset:1024
	ds_read_b128 v[194:197], v214 offset:2048
	ds_read_b128 v[198:201], v214 offset:3072
	s_barrier
	s_waitcnt lgkmcnt(0)
	s_nop 0
	s_waitcnt lgkmcnt(0)
	v_mfma_f32_16x16x32_bf16 v[10:13], v[86:89], v[130:133], v[10:13]
	v_mfma_f32_16x16x32_bf16 v[30:33], v[194:197], v[130:133], v[30:33]
	v_mfma_f32_16x16x32_bf16 v[34:37], v[86:89], v[138:141], v[34:37]
	v_mfma_f32_16x16x32_bf16 v[38:41], v[194:197], v[138:141], v[38:41]
	v_mfma_f32_16x16x32_bf16 v[42:45], v[86:89], v[170:173], v[42:45]
	v_mfma_f32_16x16x32_bf16 v[46:49], v[194:197], v[170:173], v[46:49]
	v_mfma_f32_16x16x32_bf16 v[50:53], v[86:89], v[178:181], v[50:53]
	v_mfma_f32_16x16x32_bf16 v[54:57], v[194:197], v[178:181], v[54:57]
	v_mfma_f32_16x16x32_bf16 v[10:13], v[90:93], v[134:137], v[10:13]
	v_mfma_f32_16x16x32_bf16 v[30:33], v[198:201], v[134:137], v[30:33]
	v_mfma_f32_16x16x32_bf16 v[34:37], v[90:93], v[166:169], v[34:37]
	v_mfma_f32_16x16x32_bf16 v[38:41], v[198:201], v[166:169], v[38:41]
	v_mfma_f32_16x16x32_bf16 v[42:45], v[90:93], v[174:177], v[42:45]
	v_mfma_f32_16x16x32_bf16 v[46:49], v[198:201], v[174:177], v[46:49]
	v_mfma_f32_16x16x32_bf16 v[50:53], v[90:93], v[186:189], v[50:53]
	v_mfma_f32_16x16x32_bf16 v[54:57], v[198:201], v[186:189], v[54:57]
	s_nop 0
	s_barrier
	ds_read_b128 v[130:133], v238 offset:16384
	ds_read_b128 v[134:137], v238 offset:17408
	ds_read_b128 v[138:141], v238 offset:18432
	ds_read_b128 v[166:169], v238 offset:19456
	ds_read_b128 v[170:173], v238 offset:20480
	ds_read_b128 v[174:177], v238 offset:21504
	ds_read_b128 v[178:181], v238 offset:22528
	ds_read_b128 v[186:189], v238 offset:23552
	s_waitcnt vmcnt(4)
	s_barrier
	s_waitcnt lgkmcnt(0)
	s_nop 0
	s_waitcnt lgkmcnt(0)
	v_mfma_f32_16x16x32_bf16 v[4:7], v[114:117], v[130:133], v[6:9]
	v_mfma_f32_16x16x32_bf16 v[14:17], v[114:117], v[178:181], v[14:17]
	v_mfma_f32_16x16x32_bf16 v[18:21], v[122:125], v[178:181], v[18:21]
	v_mfma_f32_16x16x32_bf16 v[4:7], v[118:121], v[134:137], v[4:7]
	v_mfma_f32_16x16x32_bf16 v[142:145], v[122:125], v[130:133], v[142:145]
	v_mfma_f32_16x16x32_bf16 v[146:149], v[114:117], v[138:141], v[146:149]
	v_mfma_f32_16x16x32_bf16 v[154:157], v[122:125], v[138:141], v[154:157]
	v_mfma_f32_16x16x32_bf16 v[158:161], v[114:117], v[170:173], v[158:161]
	v_mfma_f32_16x16x32_bf16 v[162:165], v[122:125], v[170:173], v[162:165]
	v_mfma_f32_16x16x32_bf16 v[14:17], v[118:121], v[186:189], v[14:17]
	v_mfma_f32_16x16x32_bf16 v[18:21], v[126:129], v[186:189], v[18:21]
	v_mfma_f32_16x16x32_bf16 v[142:145], v[126:129], v[134:137], v[142:145]
	v_mfma_f32_16x16x32_bf16 v[146:149], v[118:121], v[166:169], v[146:149]
	v_mfma_f32_16x16x32_bf16 v[154:157], v[126:129], v[166:169], v[154:157]
	v_mfma_f32_16x16x32_bf16 v[158:161], v[118:121], v[174:177], v[158:161]
	v_mfma_f32_16x16x32_bf16 v[162:165], v[126:129], v[174:177], v[162:165]
	s_nop 0
	s_nop 0
	v_mfma_f32_16x16x32_bf16 v[22:25], v[86:89], v[130:133], v[22:25]
	v_mfma_f32_16x16x32_bf16 v[202:205], v[90:93], v[134:137], v[22:25]
	v_mfma_f32_16x16x32_bf16 v[22:25], v[194:197], v[130:133], v[26:29]
	v_mfma_f32_16x16x32_bf16 v[128:131], v[198:201], v[134:137], v[22:25]
	v_mfma_f32_16x16x32_bf16 v[22:25], v[86:89], v[138:141], v[58:61]
	v_mfma_f32_16x16x32_bf16 v[132:135], v[90:93], v[166:169], v[22:25]
	v_mfma_f32_16x16x32_bf16 v[22:25], v[194:197], v[138:141], v[102:105]
	v_mfma_f32_16x16x32_bf16 v[136:139], v[198:201], v[166:169], v[22:25]
	v_mfma_f32_16x16x32_bf16 v[22:25], v[86:89], v[170:173], v[106:109]
	v_mfma_f32_16x16x32_bf16 v[166:169], v[90:93], v[174:177], v[22:25]
	v_mfma_f32_16x16x32_bf16 v[22:25], v[194:197], v[170:173], v[110:113]
	v_mfma_f32_16x16x32_bf16 v[170:173], v[198:201], v[174:177], v[22:25]
	v_mfma_f32_16x16x32_bf16 v[22:25], v[86:89], v[178:181], v[94:97]
	v_mfma_f32_16x16x32_bf16 v[174:177], v[90:93], v[186:189], v[22:25]
	v_mfma_f32_16x16x32_bf16 v[22:25], v[194:197], v[178:181], v[98:101]
	v_mfma_f32_16x16x32_bf16 v[178:181], v[198:201], v[186:189], v[22:25]
	s_nop 0
	s_barrier
	ds_read_b128 v[186:189], v215
	ds_read_b128 v[194:197], v215 offset:1024
	ds_read_b128 v[198:201], v215 offset:2048
	ds_read_b128 v[206:209], v215 offset:3072
	s_nop 0
	ds_read_b128 v[22:25], v238 offset:32768
	ds_read_b128 v[26:29], v238 offset:33792
	ds_read_b128 v[58:61], v238 offset:34816
	ds_read_b128 v[96:99], v238 offset:35840
	ds_read_b128 v[210:213], v238 offset:36864
	ds_read_b128 v[214:217], v238 offset:37888
	ds_read_b128 v[218:221], v238 offset:38912
	ds_read_b128 v[222:225], v238 offset:39936
	s_waitcnt vmcnt(2)
	s_barrier
	s_waitcnt lgkmcnt(0)
	s_nop 0
	s_waitcnt lgkmcnt(0)
	v_mfma_f32_16x16x32_bf16 v[0:3], v[186:189], v[22:25], v[0:3]
	v_mfma_f32_16x16x32_bf16 v[124:127], v[194:197], v[26:29], v[0:3]
	v_mfma_f32_16x16x32_bf16 v[0:3], v[198:201], v[22:25], v[62:65]
	v_mfma_f32_16x16x32_bf16 v[120:123], v[206:209], v[26:29], v[0:3]
	v_mfma_f32_16x16x32_bf16 v[0:3], v[186:189], v[58:61], v[66:69]
	v_mfma_f32_16x16x32_bf16 v[108:111], v[194:197], v[96:99], v[0:3]
	v_mfma_f32_16x16x32_bf16 v[0:3], v[198:201], v[58:61], v[70:73]
	v_mfma_f32_16x16x32_bf16 v[104:107], v[206:209], v[96:99], v[0:3]
	v_mfma_f32_16x16x32_bf16 v[0:3], v[186:189], v[210:213], v[74:77]
	v_mfma_f32_16x16x32_bf16 v[92:95], v[194:197], v[214:217], v[0:3]
	v_mfma_f32_16x16x32_bf16 v[0:3], v[198:201], v[210:213], v[78:81]
	v_mfma_f32_16x16x32_bf16 v[88:91], v[206:209], v[214:217], v[0:3]
	v_mfma_f32_16x16x32_bf16 v[0:3], v[186:189], v[218:221], v[82:85]
	v_mfma_f32_16x16x32_bf16 v[76:79], v[194:197], v[222:225], v[0:3]
	v_mfma_f32_16x16x32_bf16 v[0:3], v[198:201], v[218:221], v[190:193]
	v_mfma_f32_16x16x32_bf16 v[72:75], v[206:209], v[222:225], v[0:3]
	s_nop 0
	s_barrier
	s_nop 4
	ds_read_b128 v[0:3], v230
	ds_read_b128 v[190:193], v230 offset:1024
	ds_read_b128 v[226:229], v230 offset:2048
	ds_read_b128 v[230:233], v230 offset:3072
	s_waitcnt vmcnt(0)
	s_barrier
	s_waitcnt lgkmcnt(0)
	s_nop 0
	s_waitcnt lgkmcnt(0)
	v_mfma_f32_16x16x32_bf16 v[8:11], v[0:3], v[22:25], v[10:13]
	v_mfma_f32_16x16x32_bf16 v[116:119], v[190:193], v[26:29], v[8:11]
	v_mfma_f32_16x16x32_bf16 v[8:11], v[226:229], v[22:25], v[30:33]
	v_mfma_f32_16x16x32_bf16 v[112:115], v[230:233], v[26:29], v[8:11]
	v_mfma_f32_16x16x32_bf16 v[8:11], v[0:3], v[58:61], v[34:37]
	v_mfma_f32_16x16x32_bf16 v[100:103], v[190:193], v[96:99], v[8:11]
	v_mfma_f32_16x16x32_bf16 v[8:11], v[226:229], v[58:61], v[38:41]
	v_mfma_f32_16x16x32_bf16 v[96:99], v[230:233], v[96:99], v[8:11]
	v_mfma_f32_16x16x32_bf16 v[8:11], v[0:3], v[210:213], v[42:45]
	v_mfma_f32_16x16x32_bf16 v[84:87], v[190:193], v[214:217], v[8:11]
	v_mfma_f32_16x16x32_bf16 v[8:11], v[226:229], v[210:213], v[46:49]
	v_mfma_f32_16x16x32_bf16 v[80:83], v[230:233], v[214:217], v[8:11]
	v_mfma_f32_16x16x32_bf16 v[8:11], v[0:3], v[218:221], v[50:53]
	v_mfma_f32_16x16x32_bf16 v[68:71], v[190:193], v[222:225], v[8:11]
	v_mfma_f32_16x16x32_bf16 v[8:11], v[226:229], v[218:221], v[54:57]
	v_mfma_f32_16x16x32_bf16 v[64:67], v[230:233], v[222:225], v[8:11]
	s_nop 0
	s_barrier
	ds_read_b128 v[32:35], v238 offset:49152
	ds_read_b128 v[36:39], v238 offset:50176
	ds_read_b128 v[210:213], v238 offset:51200
	ds_read_b128 v[214:217], v238 offset:52224
	ds_read_b128 v[218:221], v238 offset:53248
	ds_read_b128 v[222:225], v238 offset:54272
	ds_read_b128 v[234:237], v238 offset:55296
	ds_read_b128 v[238:241], v238 offset:56320
	s_barrier
	s_waitcnt lgkmcnt(0)
	s_nop 0
	s_waitcnt lgkmcnt(0)
	v_mfma_f32_16x16x32_bf16 v[4:7], v[186:189], v[32:35], v[4:7]
	v_mfma_f32_16x16x32_bf16 v[60:63], v[194:197], v[36:39], v[4:7]
	v_mfma_f32_16x16x32_bf16 v[4:7], v[198:201], v[32:35], v[142:145]
	v_mfma_f32_16x16x32_bf16 v[56:59], v[206:209], v[36:39], v[4:7]
	v_mfma_f32_16x16x32_bf16 v[4:7], v[186:189], v[210:213], v[146:149]
	v_mfma_f32_16x16x32_bf16 v[44:47], v[194:197], v[214:217], v[4:7]
	v_mfma_f32_16x16x32_bf16 v[4:7], v[198:201], v[210:213], v[154:157]
	v_mfma_f32_16x16x32_bf16 v[40:43], v[206:209], v[214:217], v[4:7]
	v_mfma_f32_16x16x32_bf16 v[4:7], v[186:189], v[218:221], v[158:161]
	v_mfma_f32_16x16x32_bf16 v[28:31], v[194:197], v[222:225], v[4:7]
	v_mfma_f32_16x16x32_bf16 v[4:7], v[198:201], v[218:221], v[162:165]
	v_mfma_f32_16x16x32_bf16 v[24:27], v[206:209], v[222:225], v[4:7]
	v_mfma_f32_16x16x32_bf16 v[4:7], v[186:189], v[234:237], v[14:17]
	v_mfma_f32_16x16x32_bf16 v[12:15], v[194:197], v[238:241], v[4:7]
	v_mfma_f32_16x16x32_bf16 v[4:7], v[198:201], v[234:237], v[18:21]
	v_mfma_f32_16x16x32_bf16 v[8:11], v[206:209], v[238:241], v[4:7]
	s_nop 0
	s_nop 0
	v_mfma_f32_16x16x32_bf16 v[4:7], v[0:3], v[32:35], v[202:205]
	v_mfma_f32_16x16x32_bf16 v[52:55], v[190:193], v[36:39], v[4:7]
	v_mfma_f32_16x16x32_bf16 v[4:7], v[226:229], v[32:35], v[128:131]
	v_mfma_f32_16x16x32_bf16 v[48:51], v[230:233], v[36:39], v[4:7]
	v_mfma_f32_16x16x32_bf16 v[4:7], v[0:3], v[210:213], v[132:135]
	v_mfma_f32_16x16x32_bf16 v[36:39], v[190:193], v[214:217], v[4:7]
	v_mfma_f32_16x16x32_bf16 v[4:7], v[226:229], v[210:213], v[136:139]
	v_mfma_f32_16x16x32_bf16 v[32:35], v[230:233], v[214:217], v[4:7]
	v_mfma_f32_16x16x32_bf16 v[4:7], v[0:3], v[218:221], v[166:169]
	v_mfma_f32_16x16x32_bf16 v[20:23], v[190:193], v[222:225], v[4:7]
	v_mfma_f32_16x16x32_bf16 v[4:7], v[226:229], v[218:221], v[170:173]
	v_mfma_f32_16x16x32_bf16 v[0:3], v[0:3], v[234:237], v[174:177]
	v_mfma_f32_16x16x32_bf16 v[16:19], v[230:233], v[222:225], v[4:7]
	v_mfma_f32_16x16x32_bf16 v[4:7], v[190:193], v[238:241], v[0:3]
	v_mfma_f32_16x16x32_bf16 v[0:3], v[226:229], v[234:237], v[178:181]
	v_mfma_f32_16x16x32_bf16 v[0:3], v[230:233], v[238:241], v[0:3]
	s_nop 0
	s_cmpk_gt_u32 s3, 0xff
	s_barrier
	s_cbranch_scc1 .LBB0_639
	s_barrier

.LBB0_657:
	s_add_i32 s86, s74, s85
	s_lshl_b32 s19, s19, 12
	v_lshl_add_u64 v[16:17], v[12:13], 0, s[10:11]
	s_mov_b32 m0, s86
	s_add_i32 s84, s86, 0x2000
	s_lshl_b32 s30, s3, 13
	s_and_b32 s31, s19, 0x3000
	s_waitcnt vmcnt(4)
	s_barrier
	global_load_lds_dwordx4 v[16:17], off
	v_lshl_add_u64 v[16:17], v[10:11], 0, s[10:11]
	s_mov_b32 m0, s84
	s_add_i32 s51, s88, 0x8000
	s_add_i32 s49, s88, 0xa000
	global_load_lds_dwordx4 v[16:17], off
	v_lshl_add_u64 v[16:17], v[6:7], 0, s[10:11]
	s_mov_b32 m0, s51
	s_add_u32 s28, s26, 0x10080
	global_load_lds_dwordx4 v[16:17], off
	v_lshl_add_u64 v[16:17], v[8:9], 0, s[10:11]
	s_mov_b32 m0, s49
	s_addc_u32 s29, s27, 0
	s_add_i32 s3, s75, s85
	global_load_lds_dwordx4 v[16:17], off
	v_lshl_add_u64 v[16:17], s[28:29], 0, v[152:153]
	s_mov_b32 m0, s3
	s_add_i32 s19, s3, 0x2000
	global_load_lds_dwordx4 v[16:17], off
	v_lshl_add_u64 v[16:17], s[28:29], 0, v[4:5]
	s_mov_b32 m0, s19
	v_and_b32_e32 v15, 15, v14
	global_load_lds_dwordx4 v[16:17], off
	v_and_b32_e32 v16, 48, v14
	v_lshlrev_b32_e32 v14, 2, v14
	v_lshlrev_b32_e32 v15, 6, v15
	v_and_b32_e32 v14, 32, v14
	v_or_b32_e32 v17, v15, v16
	v_bitop3_b32 v15, v15, v14, v16 bitop3:0x36
	v_or_b32_e32 v64, s31, v15
	v_bitop3_b32 v14, v17, s30, v14 bitop3:0xde
	v_add_u32_e32 v170, s82, v64
	s_waitcnt vmcnt(6)
	s_barrier
	s_add_u32 s60, s24, 0x40080
	v_add_u32_e32 v185, 0, v14
	ds_read_b128 v[14:17], v170
	ds_read_b128 v[18:21], v170 offset:1024
	ds_read_b128 v[22:25], v170 offset:2048
	ds_read_b128 v[26:29], v170 offset:3072
	s_addc_u32 s61, s25, 0
	s_add_u32 s30, s26, 0x10100
	s_addc_u32 s31, s27, 0
	s_add_u32 s28, s24, 0x40100
	s_addc_u32 s29, s25, 0
	s_add_u32 s26, s26, 0x10180
	v_add_u32_e32 v171, s43, v64
	s_addc_u32 s27, s27, 0
	s_add_i32 s50, s88, 0xc000
	v_lshl_add_u64 v[62:63], s[60:61], 0, v[0:1]
	s_mov_b32 m0, s50
	s_add_i32 s48, s88, 0xe000
	ds_read_b128 v[30:33], v185
	ds_read_b128 v[34:37], v185 offset:1024
	ds_read_b128 v[38:41], v185 offset:2048
	ds_read_b128 v[42:45], v185 offset:3072
	ds_read_b128 v[46:49], v185 offset:4096
	ds_read_b128 v[50:53], v185 offset:5120
	ds_read_b128 v[54:57], v185 offset:6144
	ds_read_b128 v[58:61], v185 offset:7168
	global_load_lds_dwordx4 v[62:63], off
	v_lshl_add_u64 v[62:63], s[60:61], 0, v[2:3]
	s_mov_b32 m0, s48
	v_add_u32_e32 v234, s74, v64
	global_load_lds_dwordx4 v[62:63], off
	s_waitcnt lgkmcnt(8)
	s_barrier
	s_waitcnt lgkmcnt(0)
	v_add_u32_e32 v235, s75, v64
	s_nop 0
	s_waitcnt lgkmcnt(0)
	v_mfma_f32_16x16x32_bf16 v[62:65], v[14:17], v[30:33], 0
	v_mfma_f32_16x16x32_bf16 v[66:69], v[22:25], v[30:33], 0
	v_mfma_f32_16x16x32_bf16 v[70:73], v[14:17], v[38:41], 0
	v_mfma_f32_16x16x32_bf16 v[74:77], v[22:25], v[38:41], 0
	v_mfma_f32_16x16x32_bf16 v[78:81], v[14:17], v[46:49], 0
	v_mfma_f32_16x16x32_bf16 v[82:85], v[22:25], v[46:49], 0
	v_mfma_f32_16x16x32_bf16 v[86:89], v[14:17], v[54:57], 0
	v_mfma_f32_16x16x32_bf16 v[90:93], v[22:25], v[54:57], 0
	v_mfma_f32_16x16x32_bf16 v[62:65], v[18:21], v[34:37], v[62:65]
	v_mfma_f32_16x16x32_bf16 v[66:69], v[26:29], v[34:37], v[66:69]
	v_mfma_f32_16x16x32_bf16 v[70:73], v[18:21], v[42:45], v[70:73]
	v_mfma_f32_16x16x32_bf16 v[74:77], v[26:29], v[42:45], v[74:77]
	v_mfma_f32_16x16x32_bf16 v[78:81], v[18:21], v[50:53], v[78:81]
	v_mfma_f32_16x16x32_bf16 v[82:85], v[26:29], v[50:53], v[82:85]
	v_mfma_f32_16x16x32_bf16 v[86:89], v[18:21], v[58:61], v[86:89]
	v_mfma_f32_16x16x32_bf16 v[90:93], v[26:29], v[58:61], v[90:93]
	s_nop 0
	s_barrier
	s_add_i32 s60, s82, s85
	v_lshl_add_u64 v[110:111], v[12:13], 0, s[12:13]
	s_mov_b32 m0, s60
	ds_read_b128 v[94:97], v171
	ds_read_b128 v[98:101], v171 offset:1024
	ds_read_b128 v[102:105], v171 offset:2048
	ds_read_b128 v[106:109], v171 offset:3072
	global_load_lds_dwordx4 v[110:111], off
	v_lshl_add_u64 v[110:111], v[10:11], 0, s[12:13]
	s_add_i32 m0, s60, 0x2000
	s_nop 0
	global_load_lds_dwordx4 v[110:111], off
	s_barrier
	s_waitcnt lgkmcnt(0)
	s_nop 0
	s_waitcnt lgkmcnt(0)
	v_mfma_f32_16x16x32_bf16 v[110:113], v[94:97], v[30:33], 0
	v_mfma_f32_16x16x32_bf16 v[30:33], v[102:105], v[30:33], 0
	v_mfma_f32_16x16x32_bf16 v[110:113], v[98:101], v[34:37], v[110:113]
	v_mfma_f32_16x16x32_bf16 v[30:33], v[106:109], v[34:37], v[30:33]
	v_mfma_f32_16x16x32_bf16 v[34:37], v[94:97], v[38:41], 0
	v_mfma_f32_16x16x32_bf16 v[38:41], v[102:105], v[38:41], 0
	v_mfma_f32_16x16x32_bf16 v[34:37], v[98:101], v[42:45], v[34:37]
	v_mfma_f32_16x16x32_bf16 v[38:41], v[106:109], v[42:45], v[38:41]
	v_mfma_f32_16x16x32_bf16 v[42:45], v[94:97], v[46:49], 0
	v_mfma_f32_16x16x32_bf16 v[46:49], v[102:105], v[46:49], 0
	v_mfma_f32_16x16x32_bf16 v[42:45], v[98:101], v[50:53], v[42:45]
	v_mfma_f32_16x16x32_bf16 v[46:49], v[106:109], v[50:53], v[46:49]
	v_mfma_f32_16x16x32_bf16 v[50:53], v[94:97], v[54:57], 0
	v_mfma_f32_16x16x32_bf16 v[54:57], v[102:105], v[54:57], 0
	v_mfma_f32_16x16x32_bf16 v[50:53], v[98:101], v[58:61], v[50:53]
	v_mfma_f32_16x16x32_bf16 v[54:57], v[106:109], v[58:61], v[54:57]
	s_nop 0
	s_mov_b32 m0, s88
	v_lshl_add_u64 v[142:143], v[6:7], 0, s[12:13]
	s_barrier
	ds_read_b128 v[58:61], v185 offset:16384
	ds_read_b128 v[114:117], v185 offset:17408
	ds_read_b128 v[118:121], v185 offset:18432
	ds_read_b128 v[122:125], v185 offset:19456
	ds_read_b128 v[126:129], v185 offset:20480
	ds_read_b128 v[130:133], v185 offset:21504
	ds_read_b128 v[134:137], v185 offset:22528
	ds_read_b128 v[138:141], v185 offset:23552
	global_load_lds_dwordx4 v[142:143], off
	v_lshl_add_u64 v[142:143], v[8:9], 0, s[12:13]
	s_mov_b32 m0, s89
	s_nop 0
	global_load_lds_dwordx4 v[142:143], off
	s_barrier
	s_waitcnt lgkmcnt(0)
	s_nop 0
	s_waitcnt lgkmcnt(0)
	v_mfma_f32_16x16x32_bf16 v[142:145], v[14:17], v[58:61], 0
	v_mfma_f32_16x16x32_bf16 v[154:157], v[14:17], v[118:121], 0
	v_mfma_f32_16x16x32_bf16 v[162:165], v[14:17], v[126:129], 0
	v_mfma_f32_16x16x32_bf16 v[14:17], v[14:17], v[134:137], 0
	v_mfma_f32_16x16x32_bf16 v[142:145], v[18:21], v[114:117], v[142:145]
	v_mfma_f32_16x16x32_bf16 v[154:157], v[18:21], v[122:125], v[154:157]
	v_mfma_f32_16x16x32_bf16 v[162:165], v[18:21], v[130:133], v[162:165]
	v_mfma_f32_16x16x32_bf16 v[14:17], v[18:21], v[138:141], v[14:17]
	v_mfma_f32_16x16x32_bf16 v[18:21], v[22:25], v[134:137], 0
	v_mfma_f32_16x16x32_bf16 v[146:149], v[22:25], v[58:61], 0
	v_mfma_f32_16x16x32_bf16 v[158:161], v[22:25], v[118:121], 0
	v_mfma_f32_16x16x32_bf16 v[166:169], v[22:25], v[126:129], 0
	v_mfma_f32_16x16x32_bf16 v[18:21], v[26:29], v[138:141], v[18:21]
	v_mfma_f32_16x16x32_bf16 v[146:149], v[26:29], v[114:117], v[146:149]
	v_mfma_f32_16x16x32_bf16 v[158:161], v[26:29], v[122:125], v[158:161]
	v_mfma_f32_16x16x32_bf16 v[166:169], v[26:29], v[130:133], v[166:169]
	s_nop 0
	s_barrier
	s_add_i32 s60, s43, s85
	v_lshl_add_u64 v[22:23], s[30:31], 0, v[152:153]
	s_mov_b32 m0, s60
	s_nop 0
	global_load_lds_dwordx4 v[22:23], off
	v_lshl_add_u64 v[22:23], s[30:31], 0, v[4:5]
	s_add_i32 m0, s60, 0x2000
	s_nop 0
	global_load_lds_dwordx4 v[22:23], off
	s_waitcnt vmcnt(6)
	s_barrier
	s_nop 0
	v_mfma_f32_16x16x32_bf16 v[22:25], v[94:97], v[58:61], 0
	v_mfma_f32_16x16x32_bf16 v[26:29], v[102:105], v[58:61], 0
	v_mfma_f32_16x16x32_bf16 v[22:25], v[98:101], v[114:117], v[22:25]
	v_mfma_f32_16x16x32_bf16 v[26:29], v[106:109], v[114:117], v[26:29]
	v_mfma_f32_16x16x32_bf16 v[58:61], v[94:97], v[118:121], 0
	v_mfma_f32_16x16x32_bf16 v[114:117], v[102:105], v[118:121], 0
	v_mfma_f32_16x16x32_bf16 v[118:121], v[94:97], v[126:129], 0
	v_mfma_f32_16x16x32_bf16 v[94:97], v[94:97], v[134:137], 0
	v_mfma_f32_16x16x32_bf16 v[58:61], v[98:101], v[122:125], v[58:61]
	v_mfma_f32_16x16x32_bf16 v[114:117], v[106:109], v[122:125], v[114:117]
	v_mfma_f32_16x16x32_bf16 v[118:121], v[98:101], v[130:133], v[118:121]
	v_mfma_f32_16x16x32_bf16 v[122:125], v[102:105], v[126:129], 0
	v_mfma_f32_16x16x32_bf16 v[94:97], v[98:101], v[138:141], v[94:97]
	v_mfma_f32_16x16x32_bf16 v[98:101], v[102:105], v[134:137], 0
	v_mfma_f32_16x16x32_bf16 v[122:125], v[106:109], v[130:133], v[122:125]
	v_mfma_f32_16x16x32_bf16 v[98:101], v[106:109], v[138:141], v[98:101]
	s_nop 0
	s_barrier
	ds_read_b128 v[102:105], v234
	ds_read_b128 v[106:109], v234 offset:1024
	ds_read_b128 v[126:129], v234 offset:2048
	ds_read_b128 v[130:133], v234 offset:3072
	s_mov_b32 m0, s87
	v_lshl_add_u64 v[150:151], s[28:29], 0, v[0:1]
	ds_read_b128 v[134:137], v185 offset:32768
	ds_read_b128 v[138:141], v185 offset:33792
	ds_read_b128 v[174:177], v185 offset:34816
	ds_read_b128 v[178:181], v185 offset:35840
	ds_read_b128 v[186:189], v185 offset:36864
	ds_read_b128 v[190:193], v185 offset:37888
	ds_read_b128 v[194:197], v185 offset:38912
	ds_read_b128 v[198:201], v185 offset:39936
	global_load_lds_dwordx4 v[150:151], off
	v_lshl_add_u64 v[150:151], s[28:29], 0, v[2:3]
	s_mov_b32 m0, s83
	s_nop 0
	global_load_lds_dwordx4 v[150:151], off
	s_waitcnt lgkmcnt(8)
	s_barrier
	s_waitcnt lgkmcnt(0)
	s_nop 0
	s_waitcnt lgkmcnt(0)
	v_mfma_f32_16x16x32_bf16 v[62:65], v[102:105], v[134:137], v[62:65]
	v_mfma_f32_16x16x32_bf16 v[66:69], v[126:129], v[134:137], v[66:69]
	v_mfma_f32_16x16x32_bf16 v[70:73], v[102:105], v[174:177], v[70:73]
	v_mfma_f32_16x16x32_bf16 v[74:77], v[126:129], v[174:177], v[74:77]
	v_mfma_f32_16x16x32_bf16 v[78:81], v[102:105], v[186:189], v[78:81]
	v_mfma_f32_16x16x32_bf16 v[82:85], v[126:129], v[186:189], v[82:85]
	v_mfma_f32_16x16x32_bf16 v[86:89], v[102:105], v[194:197], v[86:89]
	v_mfma_f32_16x16x32_bf16 v[90:93], v[126:129], v[194:197], v[90:93]
	v_mfma_f32_16x16x32_bf16 v[62:65], v[106:109], v[138:141], v[62:65]
	v_mfma_f32_16x16x32_bf16 v[66:69], v[130:133], v[138:141], v[66:69]
	v_mfma_f32_16x16x32_bf16 v[70:73], v[106:109], v[178:181], v[70:73]
	v_mfma_f32_16x16x32_bf16 v[74:77], v[130:133], v[178:181], v[74:77]
	v_mfma_f32_16x16x32_bf16 v[78:81], v[106:109], v[190:193], v[78:81]
	v_mfma_f32_16x16x32_bf16 v[82:85], v[130:133], v[190:193], v[82:85]
	v_mfma_f32_16x16x32_bf16 v[86:89], v[106:109], v[198:201], v[86:89]
	v_mfma_f32_16x16x32_bf16 v[90:93], v[130:133], v[198:201], v[90:93]
	s_nop 0
	s_barrier
	s_mov_b32 m0, s86
	v_lshl_add_u64 v[12:13], v[12:13], 0, s[14:15]
	ds_read_b128 v[202:205], v235
	ds_read_b128 v[206:209], v235 offset:1024
	ds_read_b128 v[210:213], v235 offset:2048
	ds_read_b128 v[214:217], v235 offset:3072
	global_load_lds_dwordx4 v[12:13], off
	v_lshl_add_u64 v[10:11], v[10:11], 0, s[14:15]
	s_mov_b32 m0, s84
	s_nop 0
	global_load_lds_dwordx4 v[10:11], off
	s_barrier
	s_waitcnt lgkmcnt(0)
	s_nop 0
	s_waitcnt lgkmcnt(0)
	v_mfma_f32_16x16x32_bf16 v[10:13], v[202:205], v[134:137], v[110:113]
	v_mfma_f32_16x16x32_bf16 v[30:33], v[210:213], v[134:137], v[30:33]
	v_mfma_f32_16x16x32_bf16 v[34:37], v[202:205], v[174:177], v[34:37]
	v_mfma_f32_16x16x32_bf16 v[38:41], v[210:213], v[174:177], v[38:41]
	v_mfma_f32_16x16x32_bf16 v[42:45], v[202:205], v[186:189], v[42:45]
	v_mfma_f32_16x16x32_bf16 v[46:49], v[210:213], v[186:189], v[46:49]
	v_mfma_f32_16x16x32_bf16 v[50:53], v[202:205], v[194:197], v[50:53]
	v_mfma_f32_16x16x32_bf16 v[54:57], v[210:213], v[194:197], v[54:57]
	v_mfma_f32_16x16x32_bf16 v[10:13], v[206:209], v[138:141], v[10:13]
	v_mfma_f32_16x16x32_bf16 v[30:33], v[214:217], v[138:141], v[30:33]
	v_mfma_f32_16x16x32_bf16 v[34:37], v[206:209], v[178:181], v[34:37]
	v_mfma_f32_16x16x32_bf16 v[38:41], v[214:217], v[178:181], v[38:41]
	v_mfma_f32_16x16x32_bf16 v[42:45], v[206:209], v[190:193], v[42:45]
	v_mfma_f32_16x16x32_bf16 v[46:49], v[214:217], v[190:193], v[46:49]
	v_mfma_f32_16x16x32_bf16 v[50:53], v[206:209], v[198:201], v[50:53]
	v_mfma_f32_16x16x32_bf16 v[54:57], v[214:217], v[198:201], v[54:57]
	s_nop 0
	s_mov_b32 m0, s51
	v_lshl_add_u64 v[6:7], v[6:7], 0, s[14:15]
	s_barrier
	ds_read_b128 v[110:113], v185 offset:49152
	ds_read_b128 v[134:137], v185 offset:50176
	ds_read_b128 v[138:141], v185 offset:51200
	ds_read_b128 v[174:177], v185 offset:52224
	ds_read_b128 v[178:181], v185 offset:53248
	ds_read_b128 v[186:189], v185 offset:54272
	ds_read_b128 v[190:193], v185 offset:55296
	ds_read_b128 v[194:197], v185 offset:56320
	global_load_lds_dwordx4 v[6:7], off
	v_lshl_add_u64 v[6:7], v[8:9], 0, s[14:15]
	s_mov_b32 m0, s49
	s_nop 0
	global_load_lds_dwordx4 v[6:7], off
	s_barrier
	s_waitcnt lgkmcnt(0)
	s_nop 0
	s_waitcnt lgkmcnt(0)
	v_mfma_f32_16x16x32_bf16 v[6:9], v[102:105], v[110:113], v[142:145]
	v_mfma_f32_16x16x32_bf16 v[14:17], v[102:105], v[190:193], v[14:17]
	v_mfma_f32_16x16x32_bf16 v[18:21], v[126:129], v[190:193], v[18:21]
	v_mfma_f32_16x16x32_bf16 v[6:9], v[106:109], v[134:137], v[6:9]
	v_mfma_f32_16x16x32_bf16 v[142:145], v[126:129], v[110:113], v[146:149]
	v_mfma_f32_16x16x32_bf16 v[146:149], v[102:105], v[138:141], v[154:157]
	v_mfma_f32_16x16x32_bf16 v[154:157], v[126:129], v[138:141], v[158:161]
	v_mfma_f32_16x16x32_bf16 v[158:161], v[102:105], v[178:181], v[162:165]
	v_mfma_f32_16x16x32_bf16 v[162:165], v[126:129], v[178:181], v[166:169]
	v_mfma_f32_16x16x32_bf16 v[14:17], v[106:109], v[194:197], v[14:17]
	v_mfma_f32_16x16x32_bf16 v[18:21], v[130:133], v[194:197], v[18:21]
	v_mfma_f32_16x16x32_bf16 v[142:145], v[130:133], v[134:137], v[142:145]
	v_mfma_f32_16x16x32_bf16 v[146:149], v[106:109], v[174:177], v[146:149]
	v_mfma_f32_16x16x32_bf16 v[154:157], v[130:133], v[174:177], v[154:157]
	v_mfma_f32_16x16x32_bf16 v[158:161], v[106:109], v[186:189], v[158:161]
	v_mfma_f32_16x16x32_bf16 v[162:165], v[130:133], v[186:189], v[162:165]
	s_nop 0
	s_barrier
	s_mov_b32 m0, s3
	v_lshl_add_u64 v[102:103], s[26:27], 0, v[152:153]
	global_load_lds_dwordx4 v[102:103], off
	v_lshl_add_u64 v[4:5], s[26:27], 0, v[4:5]
	s_mov_b32 m0, s19
	s_nop 0
	global_load_lds_dwordx4 v[4:5], off
	s_waitcnt vmcnt(6)
	s_barrier
	s_nop 0
	v_mfma_f32_16x16x32_bf16 v[22:25], v[202:205], v[110:113], v[22:25]
	v_mfma_f32_16x16x32_bf16 v[26:29], v[210:213], v[110:113], v[26:29]
	v_mfma_f32_16x16x32_bf16 v[58:61], v[202:205], v[138:141], v[58:61]
	v_mfma_f32_16x16x32_bf16 v[102:105], v[210:213], v[138:141], v[114:117]
	v_mfma_f32_16x16x32_bf16 v[106:109], v[202:205], v[178:181], v[118:121]
	v_mfma_f32_16x16x32_bf16 v[94:97], v[202:205], v[190:193], v[94:97]
	v_mfma_f32_16x16x32_bf16 v[98:101], v[210:213], v[190:193], v[98:101]
	v_mfma_f32_16x16x32_bf16 v[22:25], v[206:209], v[134:137], v[22:25]
	v_mfma_f32_16x16x32_bf16 v[26:29], v[214:217], v[134:137], v[26:29]
	v_mfma_f32_16x16x32_bf16 v[58:61], v[206:209], v[174:177], v[58:61]
	v_mfma_f32_16x16x32_bf16 v[102:105], v[214:217], v[174:177], v[102:105]
	v_mfma_f32_16x16x32_bf16 v[106:109], v[206:209], v[186:189], v[106:109]
	v_mfma_f32_16x16x32_bf16 v[110:113], v[210:213], v[178:181], v[122:125]
	v_mfma_f32_16x16x32_bf16 v[94:97], v[206:209], v[194:197], v[94:97]
	v_mfma_f32_16x16x32_bf16 v[98:101], v[214:217], v[194:197], v[98:101]
	v_mfma_f32_16x16x32_bf16 v[110:113], v[214:217], v[186:189], v[110:113]
	s_nop 0
	s_add_u32 s24, s24, 0x40180
	s_addc_u32 s25, s25, 0
	s_mov_b32 m0, s50
	v_lshl_add_u64 v[0:1], s[24:25], 0, v[0:1]
	s_barrier
	ds_read_b128 v[114:117], v170
	ds_read_b128 v[118:121], v170 offset:1024
	ds_read_b128 v[122:125], v170 offset:2048
	ds_read_b128 v[126:129], v170 offset:3072
	ds_read_b128 v[130:133], v185
	ds_read_b128 v[134:137], v185 offset:1024
	ds_read_b128 v[138:141], v185 offset:2048
	ds_read_b128 v[166:169], v185 offset:3072
	ds_read_b128 v[174:177], v185 offset:4096
	ds_read_b128 v[178:181], v185 offset:5120
	ds_read_b128 v[186:189], v185 offset:6144
	ds_read_b128 v[190:193], v185 offset:7168
	global_load_lds_dwordx4 v[0:1], off
	v_lshl_add_u64 v[0:1], s[24:25], 0, v[2:3]
	s_mov_b32 m0, s48
	s_nop 0
	global_load_lds_dwordx4 v[0:1], off
	s_barrier
	s_waitcnt lgkmcnt(0)
	s_nop 0
	s_waitcnt lgkmcnt(0)
	v_mfma_f32_16x16x32_bf16 v[0:3], v[114:117], v[130:133], v[62:65]
	v_mfma_f32_16x16x32_bf16 v[62:65], v[122:125], v[130:133], v[66:69]
	v_mfma_f32_16x16x32_bf16 v[66:69], v[114:117], v[138:141], v[70:73]
	v_mfma_f32_16x16x32_bf16 v[70:73], v[122:125], v[138:141], v[74:77]
	v_mfma_f32_16x16x32_bf16 v[74:77], v[114:117], v[174:177], v[78:81]
	v_mfma_f32_16x16x32_bf16 v[78:81], v[122:125], v[174:177], v[82:85]
	v_mfma_f32_16x16x32_bf16 v[82:85], v[114:117], v[186:189], v[86:89]
	v_mfma_f32_16x16x32_bf16 v[86:89], v[122:125], v[186:189], v[90:93]
	v_mfma_f32_16x16x32_bf16 v[0:3], v[118:121], v[134:137], v[0:3]
	v_mfma_f32_16x16x32_bf16 v[62:65], v[126:129], v[134:137], v[62:65]
	v_mfma_f32_16x16x32_bf16 v[66:69], v[118:121], v[166:169], v[66:69]
	v_mfma_f32_16x16x32_bf16 v[70:73], v[126:129], v[166:169], v[70:73]
	v_mfma_f32_16x16x32_bf16 v[74:77], v[118:121], v[178:181], v[74:77]
	v_mfma_f32_16x16x32_bf16 v[78:81], v[126:129], v[178:181], v[78:81]
	v_mfma_f32_16x16x32_bf16 v[82:85], v[118:121], v[190:193], v[82:85]
	v_mfma_f32_16x16x32_bf16 v[86:89], v[126:129], v[190:193], v[86:89]
	s_nop 0
	s_barrier
	ds_read_b128 v[90:93], v171
	ds_read_b128 v[194:197], v171 offset:1024
	ds_read_b128 v[198:201], v171 offset:2048
	ds_read_b128 v[202:205], v171 offset:3072
	s_barrier
	s_waitcnt lgkmcnt(0)
	s_nop 0
	s_waitcnt lgkmcnt(0)
	v_mfma_f32_16x16x32_bf16 v[10:13], v[90:93], v[130:133], v[10:13]
	v_mfma_f32_16x16x32_bf16 v[206:209], v[194:197], v[134:137], v[10:13]
	v_mfma_f32_16x16x32_bf16 v[10:13], v[198:201], v[130:133], v[30:33]
	v_mfma_f32_16x16x32_bf16 v[30:33], v[202:205], v[134:137], v[10:13]
	v_mfma_f32_16x16x32_bf16 v[10:13], v[90:93], v[138:141], v[34:37]
	v_mfma_f32_16x16x32_bf16 v[34:37], v[194:197], v[166:169], v[10:13]
	v_mfma_f32_16x16x32_bf16 v[10:13], v[198:201], v[138:141], v[38:41]
	v_mfma_f32_16x16x32_bf16 v[38:41], v[202:205], v[166:169], v[10:13]
	v_mfma_f32_16x16x32_bf16 v[10:13], v[90:93], v[174:177], v[42:45]
	v_mfma_f32_16x16x32_bf16 v[42:45], v[194:197], v[178:181], v[10:13]
	v_mfma_f32_16x16x32_bf16 v[10:13], v[198:201], v[174:177], v[46:49]
	v_mfma_f32_16x16x32_bf16 v[46:49], v[202:205], v[178:181], v[10:13]
	v_mfma_f32_16x16x32_bf16 v[10:13], v[90:93], v[186:189], v[50:53]
	v_mfma_f32_16x16x32_bf16 v[50:53], v[194:197], v[190:193], v[10:13]
	v_mfma_f32_16x16x32_bf16 v[10:13], v[198:201], v[186:189], v[54:57]
	v_mfma_f32_16x16x32_bf16 v[136:139], v[202:205], v[190:193], v[10:13]
	s_nop 0
	s_barrier
	s_nop 4
	ds_read_b128 v[10:13], v185 offset:16384
	ds_read_b128 v[54:57], v185 offset:17408
	ds_read_b128 v[130:133], v185 offset:18432
	ds_read_b128 v[166:169], v185 offset:19456
	ds_read_b128 v[174:177], v185 offset:20480
	ds_read_b128 v[178:181], v185 offset:21504
	ds_read_b128 v[186:189], v185 offset:22528
	ds_read_b128 v[190:193], v185 offset:23552
	s_waitcnt vmcnt(4)
	s_barrier
	s_waitcnt lgkmcnt(0)
	s_nop 0
	s_waitcnt lgkmcnt(0)
	v_mfma_f32_16x16x32_bf16 v[4:7], v[114:117], v[10:13], v[6:9]
	v_mfma_f32_16x16x32_bf16 v[210:213], v[118:121], v[54:57], v[4:7]
	v_mfma_f32_16x16x32_bf16 v[4:7], v[122:125], v[10:13], v[142:145]
	v_mfma_f32_16x16x32_bf16 v[140:143], v[126:129], v[54:57], v[4:7]
	v_mfma_f32_16x16x32_bf16 v[4:7], v[114:117], v[130:133], v[146:149]
	v_mfma_f32_16x16x32_bf16 v[144:147], v[118:121], v[166:169], v[4:7]
	v_mfma_f32_16x16x32_bf16 v[4:7], v[122:125], v[130:133], v[154:157]
	v_mfma_f32_16x16x32_bf16 v[148:151], v[126:129], v[166:169], v[4:7]
	v_mfma_f32_16x16x32_bf16 v[4:7], v[114:117], v[174:177], v[158:161]
	v_mfma_f32_16x16x32_bf16 v[154:157], v[118:121], v[178:181], v[4:7]
	v_mfma_f32_16x16x32_bf16 v[4:7], v[122:125], v[174:177], v[162:165]
	v_mfma_f32_16x16x32_bf16 v[158:161], v[126:129], v[178:181], v[4:7]
	v_mfma_f32_16x16x32_bf16 v[4:7], v[114:117], v[186:189], v[14:17]
	v_mfma_f32_16x16x32_bf16 v[162:165], v[118:121], v[190:193], v[4:7]
	v_mfma_f32_16x16x32_bf16 v[4:7], v[122:125], v[186:189], v[18:21]
	v_mfma_f32_16x16x32_bf16 v[214:217], v[126:129], v[190:193], v[4:7]
	s_nop 0
	s_nop 0
	v_mfma_f32_16x16x32_bf16 v[4:7], v[90:93], v[10:13], v[22:25]
	v_mfma_f32_16x16x32_bf16 v[218:221], v[194:197], v[54:57], v[4:7]
	v_mfma_f32_16x16x32_bf16 v[4:7], v[198:201], v[10:13], v[26:29]
	v_mfma_f32_16x16x32_bf16 v[222:225], v[202:205], v[54:57], v[4:7]
	v_mfma_f32_16x16x32_bf16 v[4:7], v[90:93], v[130:133], v[58:61]
	v_mfma_f32_16x16x32_bf16 v[226:229], v[194:197], v[166:169], v[4:7]
	v_mfma_f32_16x16x32_bf16 v[4:7], v[198:201], v[130:133], v[102:105]
	v_mfma_f32_16x16x32_bf16 v[166:169], v[202:205], v[166:169], v[4:7]
	v_mfma_f32_16x16x32_bf16 v[4:7], v[90:93], v[174:177], v[106:109]
	v_mfma_f32_16x16x32_bf16 v[230:233], v[194:197], v[178:181], v[4:7]
	v_mfma_f32_16x16x32_bf16 v[4:7], v[198:201], v[174:177], v[110:113]
	v_mfma_f32_16x16x32_bf16 v[108:111], v[202:205], v[178:181], v[4:7]
	v_mfma_f32_16x16x32_bf16 v[4:7], v[90:93], v[186:189], v[94:97]
	v_mfma_f32_16x16x32_bf16 v[112:115], v[194:197], v[190:193], v[4:7]
	v_mfma_f32_16x16x32_bf16 v[4:7], v[198:201], v[186:189], v[98:101]
	v_mfma_f32_16x16x32_bf16 v[174:177], v[202:205], v[190:193], v[4:7]
	s_nop 0
	s_barrier
	ds_read_b128 v[16:19], v234
	ds_read_b128 v[20:23], v234 offset:1024
	ds_read_b128 v[90:93], v234 offset:2048
	ds_read_b128 v[94:97], v234 offset:3072
	ds_read_b128 v[24:27], v185 offset:32768
	ds_read_b128 v[54:57], v185 offset:33792
	ds_read_b128 v[58:61], v185 offset:34816
	ds_read_b128 v[178:181], v185 offset:35840
	ds_read_b128 v[186:189], v185 offset:36864
	ds_read_b128 v[190:193], v185 offset:37888
	ds_read_b128 v[194:197], v185 offset:38912
	ds_read_b128 v[198:201], v185 offset:39936
	s_waitcnt vmcnt(2)
	s_barrier
	s_waitcnt lgkmcnt(0)
	s_nop 0
	s_waitcnt lgkmcnt(0)
	v_mfma_f32_16x16x32_bf16 v[0:3], v[16:19], v[24:27], v[0:3]
	v_mfma_f32_16x16x32_bf16 v[104:107], v[20:23], v[54:57], v[0:3]
	v_mfma_f32_16x16x32_bf16 v[0:3], v[90:93], v[24:27], v[62:65]
	v_mfma_f32_16x16x32_bf16 v[100:103], v[94:97], v[54:57], v[0:3]
	v_mfma_f32_16x16x32_bf16 v[0:3], v[16:19], v[58:61], v[66:69]
	v_mfma_f32_16x16x32_bf16 v[120:123], v[20:23], v[178:181], v[0:3]
	v_mfma_f32_16x16x32_bf16 v[0:3], v[90:93], v[58:61], v[70:73]
	v_mfma_f32_16x16x32_bf16 v[116:119], v[94:97], v[178:181], v[0:3]
	v_mfma_f32_16x16x32_bf16 v[0:3], v[16:19], v[186:189], v[74:77]
	v_mfma_f32_16x16x32_bf16 v[8:11], v[20:23], v[190:193], v[0:3]
	v_mfma_f32_16x16x32_bf16 v[0:3], v[90:93], v[186:189], v[78:81]
	v_mfma_f32_16x16x32_bf16 v[12:15], v[94:97], v[190:193], v[0:3]
	v_mfma_f32_16x16x32_bf16 v[0:3], v[16:19], v[194:197], v[82:85]
	v_mfma_f32_16x16x32_bf16 v[4:7], v[90:93], v[194:197], v[86:89]
	v_mfma_f32_16x16x32_bf16 v[0:3], v[20:23], v[198:201], v[0:3]
	v_mfma_f32_16x16x32_bf16 v[4:7], v[94:97], v[198:201], v[4:7]
	s_nop 0
	s_barrier
	ds_read_b128 v[68:71], v235
	ds_read_b128 v[72:75], v235 offset:1024
	ds_read_b128 v[202:205], v235 offset:2048
	ds_read_b128 v[234:237], v235 offset:3072
	s_waitcnt vmcnt(0)
	s_barrier
	s_waitcnt lgkmcnt(0)
	s_nop 0
	s_waitcnt lgkmcnt(0)
	v_mfma_f32_16x16x32_bf16 v[62:65], v[68:71], v[24:27], v[206:209]
	v_mfma_f32_16x16x32_bf16 v[24:27], v[202:205], v[24:27], v[30:33]
	v_mfma_f32_16x16x32_bf16 v[124:127], v[234:237], v[54:57], v[24:27]
	v_mfma_f32_16x16x32_bf16 v[24:27], v[68:71], v[58:61], v[34:37]
	v_mfma_f32_16x16x32_bf16 v[128:131], v[72:75], v[178:181], v[24:27]
	v_mfma_f32_16x16x32_bf16 v[24:27], v[202:205], v[58:61], v[38:41]
	v_mfma_f32_16x16x32_bf16 v[132:135], v[72:75], v[54:57], v[62:65]
	v_mfma_f32_16x16x32_bf16 v[56:59], v[234:237], v[178:181], v[24:27]
	v_mfma_f32_16x16x32_bf16 v[24:27], v[68:71], v[186:189], v[42:45]
	v_mfma_f32_16x16x32_bf16 v[40:43], v[72:75], v[190:193], v[24:27]
	v_mfma_f32_16x16x32_bf16 v[24:27], v[202:205], v[186:189], v[46:49]
	v_mfma_f32_16x16x32_bf16 v[44:47], v[234:237], v[190:193], v[24:27]
	v_mfma_f32_16x16x32_bf16 v[24:27], v[68:71], v[194:197], v[50:53]
	v_mfma_f32_16x16x32_bf16 v[28:31], v[202:205], v[194:197], v[136:139]
	v_mfma_f32_16x16x32_bf16 v[24:27], v[72:75], v[198:201], v[24:27]
	v_mfma_f32_16x16x32_bf16 v[28:31], v[234:237], v[198:201], v[28:31]
	s_nop 0
	s_barrier
	ds_read_b128 v[76:79], v185 offset:49152
	ds_read_b128 v[80:83], v185 offset:50176
	ds_read_b128 v[136:139], v185 offset:51200
	ds_read_b128 v[178:181], v185 offset:52224
	ds_read_b128 v[186:189], v185 offset:53248
	ds_read_b128 v[190:193], v185 offset:54272
	ds_read_b128 v[194:197], v185 offset:55296
	ds_read_b128 v[198:201], v185 offset:56320
	s_barrier
	s_waitcnt lgkmcnt(0)
	s_nop 0
	s_waitcnt lgkmcnt(0)
	v_mfma_f32_16x16x32_bf16 v[32:35], v[16:19], v[76:79], v[210:213]
	v_mfma_f32_16x16x32_bf16 v[60:63], v[20:23], v[80:83], v[32:35]
	v_mfma_f32_16x16x32_bf16 v[32:35], v[90:93], v[76:79], v[140:143]
	v_mfma_f32_16x16x32_bf16 v[64:67], v[94:97], v[80:83], v[32:35]
	v_mfma_f32_16x16x32_bf16 v[32:35], v[16:19], v[136:139], v[144:147]
	v_mfma_f32_16x16x32_bf16 v[48:51], v[20:23], v[178:181], v[32:35]
	v_mfma_f32_16x16x32_bf16 v[32:35], v[90:93], v[136:139], v[148:151]
	v_mfma_f32_16x16x32_bf16 v[52:55], v[94:97], v[178:181], v[32:35]
	v_mfma_f32_16x16x32_bf16 v[32:35], v[16:19], v[186:189], v[154:157]
	v_mfma_f32_16x16x32_bf16 v[16:19], v[16:19], v[194:197], v[162:165]
	v_mfma_f32_16x16x32_bf16 v[32:35], v[20:23], v[190:193], v[32:35]
	v_mfma_f32_16x16x32_bf16 v[36:39], v[90:93], v[186:189], v[158:161]
	v_mfma_f32_16x16x32_bf16 v[16:19], v[20:23], v[198:201], v[16:19]
	v_mfma_f32_16x16x32_bf16 v[20:23], v[90:93], v[194:197], v[214:217]
	v_mfma_f32_16x16x32_bf16 v[36:39], v[94:97], v[190:193], v[36:39]
	v_mfma_f32_16x16x32_bf16 v[20:23], v[94:97], v[198:201], v[20:23]
	s_nop 0
	s_nop 0
	v_mfma_f32_16x16x32_bf16 v[84:87], v[68:71], v[76:79], v[218:221]
	v_mfma_f32_16x16x32_bf16 v[76:79], v[202:205], v[76:79], v[222:225]
	v_mfma_f32_16x16x32_bf16 v[96:99], v[234:237], v[80:83], v[76:79]
	v_mfma_f32_16x16x32_bf16 v[76:79], v[68:71], v[136:139], v[226:229]
	v_mfma_f32_16x16x32_bf16 v[92:95], v[72:75], v[80:83], v[84:87]
	v_mfma_f32_16x16x32_bf16 v[84:87], v[72:75], v[178:181], v[76:79]
	v_mfma_f32_16x16x32_bf16 v[76:79], v[202:205], v[136:139], v[166:169]
	v_mfma_f32_16x16x32_bf16 v[88:91], v[234:237], v[178:181], v[76:79]
	v_mfma_f32_16x16x32_bf16 v[76:79], v[68:71], v[186:189], v[230:233]
	v_mfma_f32_16x16x32_bf16 v[68:71], v[68:71], v[194:197], v[112:115]
	v_mfma_f32_16x16x32_bf16 v[76:79], v[72:75], v[190:193], v[76:79]
	v_mfma_f32_16x16x32_bf16 v[80:83], v[202:205], v[186:189], v[108:111]
	v_mfma_f32_16x16x32_bf16 v[68:71], v[72:75], v[198:201], v[68:71]
	v_mfma_f32_16x16x32_bf16 v[72:75], v[202:205], v[194:197], v[174:177]
	v_mfma_f32_16x16x32_bf16 v[80:83], v[234:237], v[190:193], v[80:83]
	v_mfma_f32_16x16x32_bf16 v[72:75], v[234:237], v[198:201], v[72:75]
	s_nop 0
	s_cmpk_gt_u32 s2, 0xff
	s_barrier
	s_cbranch_scc1 .LBB0_659
	s_barrier

.LBB0_661:
	s_waitcnt lgkmcnt(0)
	v_pk_mul_f32 v[112:113], v[100:101], v[158:159] op_sel_hi:[1,0]
	v_pk_mul_f32 v[100:101], v[132:133], v[158:159] op_sel_hi:[1,0]
	v_mov_b32_e32 v132, v159
	s_add_i32 s81, s74, s19
	v_pk_mul_f32 v[108:109], v[104:105], v[158:159] op_sel_hi:[1,0]
	v_pk_mul_f32 v[104:105], v[124:125], v[158:159] op_sel_hi:[1,0]
	v_pk_mul_f32 v[124:125], v[116:117], v[132:133] op_sel_hi:[1,0]
	v_pk_mul_f32 v[116:117], v[128:129], v[132:133] op_sel_hi:[1,0]
	s_lshl_b32 s25, s25, 12
	v_lshl_add_u64 v[128:129], v[148:149], 0, s[10:11]
	s_mov_b32 m0, s81
	s_add_i32 s51, s81, 0x2000
	s_lshl_b32 s26, s24, 13
	s_and_b32 s27, s25, 0x3000
	s_waitcnt vmcnt(4)
	s_barrier
	global_load_lds_dwordx4 v[128:129], off
	v_lshl_add_u64 v[128:129], v[146:147], 0, s[10:11]
	s_mov_b32 m0, s51
	s_add_i32 s50, s29, 0x8000
	s_add_i32 s49, s29, 0xa000
	global_load_lds_dwordx4 v[128:129], off
	v_lshl_add_u64 v[128:129], v[142:143], 0, s[10:11]
	s_mov_b32 m0, s50
	s_add_u32 s24, s0, 0x10080
	global_load_lds_dwordx4 v[128:129], off
	v_lshl_add_u64 v[128:129], v[144:145], 0, s[10:11]
	s_mov_b32 m0, s49
	s_addc_u32 s25, s1, 0
	s_add_i32 s31, s75, s19
	global_load_lds_dwordx4 v[128:129], off
	v_lshl_add_u64 v[128:129], s[24:25], 0, v[152:153]
	s_mov_b32 m0, s31
	s_add_i32 s48, s31, 0x2000
	global_load_lds_dwordx4 v[128:129], off
	v_lshl_add_u64 v[128:129], s[24:25], 0, v[140:141]
	s_mov_b32 m0, s48
	v_pk_mul_f32 v[110:111], v[106:107], v[158:159] op_sel_hi:[1,0]
	global_load_lds_dwordx4 v[128:129], off
	v_mov_b32_e32 v128, v157
	v_pk_mul_f32 v[2:3], v[2:3], v[128:129] op_sel_hi:[1,0]
	v_pk_mul_f32 v[0:1], v[0:1], v[128:129] op_sel_hi:[1,0]
	v_pk_mul_f32 v[6:7], v[6:7], v[128:129] op_sel_hi:[1,0]
	v_pk_mul_f32 v[4:5], v[4:5], v[128:129] op_sel_hi:[1,0]
	v_pk_mul_f32 v[26:27], v[26:27], v[128:129] op_sel_hi:[1,0]
	v_pk_mul_f32 v[24:25], v[24:25], v[128:129] op_sel_hi:[1,0]
	v_pk_mul_f32 v[30:31], v[30:31], v[128:129] op_sel_hi:[1,0]
	v_pk_mul_f32 v[28:29], v[28:29], v[128:129] op_sel_hi:[1,0]
	v_mov_b32_e32 v128, v155
	v_pk_mul_f32 v[50:51], v[50:51], v[128:129] op_sel_hi:[1,0]
	v_pk_mul_f32 v[48:49], v[48:49], v[128:129] op_sel_hi:[1,0]
	v_pk_mul_f32 v[54:55], v[54:55], v[128:129] op_sel_hi:[1,0]
	v_pk_mul_f32 v[52:53], v[52:53], v[128:129] op_sel_hi:[1,0]
	v_pk_mul_f32 v[86:87], v[86:87], v[128:129] op_sel_hi:[1,0]
	v_pk_mul_f32 v[84:85], v[84:85], v[128:129] op_sel_hi:[1,0]
	v_pk_mul_f32 v[90:91], v[90:91], v[128:129] op_sel_hi:[1,0]
	v_pk_mul_f32 v[88:89], v[88:89], v[128:129] op_sel_hi:[1,0]
	v_mov_b32_e32 v128, v151
	v_pk_mul_f32 v[106:107], v[126:127], v[158:159] op_sel_hi:[1,0]
	v_pk_mul_f32 v[126:127], v[118:119], v[132:133] op_sel_hi:[1,0]
	v_pk_mul_f32 v[118:119], v[130:131], v[132:133] op_sel_hi:[1,0]
	v_pk_mul_f32 v[18:19], v[18:19], v[128:129] op_sel_hi:[1,0]
	v_pk_mul_f32 v[16:17], v[16:17], v[128:129] op_sel_hi:[1,0]
	v_pk_mul_f32 v[22:23], v[22:23], v[128:129] op_sel_hi:[1,0]
	v_pk_mul_f32 v[20:21], v[20:21], v[128:129] op_sel_hi:[1,0]
	v_pk_mul_f32 v[70:71], v[70:71], v[128:129] op_sel_hi:[1,0]
	v_pk_mul_f32 v[68:69], v[68:69], v[128:129] op_sel_hi:[1,0]
	v_pk_mul_f32 v[74:75], v[74:75], v[128:129] op_sel_hi:[1,0]
	v_pk_mul_f32 v[72:73], v[72:73], v[128:129] op_sel_hi:[1,0]
	v_and_b32_e32 v128, 15, v160
	v_lshlrev_b32_e32 v131, 2, v160
	v_and_b32_e32 v129, 48, v160
	v_lshlrev_b32_e32 v128, 6, v128
	v_and_b32_e32 v131, 32, v131
	v_or_b32_e32 v130, v128, v129
	v_bitop3_b32 v128, v128, v131, v129 bitop3:0x36
	v_or_b32_e32 v170, s27, v128
	v_bitop3_b32 v129, v130, s26, v131 bitop3:0xde
	v_add_u32_e32 v171, s82, v170
	v_pk_mul_f32 v[114:115], v[102:103], v[158:159] op_sel_hi:[1,0]
	v_pk_mul_f32 v[102:103], v[134:135], v[158:159] op_sel_hi:[1,0]
	v_pk_mul_f32 v[122:123], v[122:123], v[132:133] op_sel_hi:[1,0]
	v_pk_mul_f32 v[120:121], v[120:121], v[132:133] op_sel_hi:[1,0]
	v_pk_mul_f32 v[58:59], v[58:59], v[132:133] op_sel_hi:[1,0]
	v_pk_mul_f32 v[56:57], v[56:57], v[132:133] op_sel_hi:[1,0]
	v_pk_mul_f32 v[10:11], v[10:11], v[156:157] op_sel_hi:[1,0]
	v_pk_mul_f32 v[8:9], v[8:9], v[156:157] op_sel_hi:[1,0]
	v_pk_mul_f32 v[14:15], v[14:15], v[156:157] op_sel_hi:[1,0]
	v_pk_mul_f32 v[12:13], v[12:13], v[156:157] op_sel_hi:[1,0]
	v_pk_mul_f32 v[42:43], v[42:43], v[156:157] op_sel_hi:[1,0]
	v_pk_mul_f32 v[40:41], v[40:41], v[156:157] op_sel_hi:[1,0]
	v_pk_mul_f32 v[46:47], v[46:47], v[156:157] op_sel_hi:[1,0]
	v_pk_mul_f32 v[44:45], v[44:45], v[156:157] op_sel_hi:[1,0]
	v_pk_mul_f32 v[62:63], v[62:63], v[154:155] op_sel_hi:[1,0]
	v_pk_mul_f32 v[60:61], v[60:61], v[154:155] op_sel_hi:[1,0]
	v_pk_mul_f32 v[66:67], v[66:67], v[154:155] op_sel_hi:[1,0]
	v_pk_mul_f32 v[64:65], v[64:65], v[154:155] op_sel_hi:[1,0]
	v_pk_mul_f32 v[94:95], v[94:95], v[154:155] op_sel_hi:[1,0]
	v_pk_mul_f32 v[92:93], v[92:93], v[154:155] op_sel_hi:[1,0]
	v_pk_mul_f32 v[98:99], v[98:99], v[154:155] op_sel_hi:[1,0]
	v_pk_mul_f32 v[96:97], v[96:97], v[154:155] op_sel_hi:[1,0]
	s_waitcnt vmcnt(6)
	s_barrier
	s_add_u32 s60, s22, 0x10080
	v_add_u32_e32 v230, 0, v129
	ds_read_b128 v[128:131], v171
	ds_read_b128 v[132:135], v171 offset:1024
	ds_read_b128 v[154:157], v171 offset:2048
	ds_read_b128 v[158:161], v171 offset:3072
	s_addc_u32 s61, s23, 0
	s_add_u32 s26, s0, 0x10100
	s_addc_u32 s27, s1, 0
	s_add_u32 s24, s22, 0x10100
	s_addc_u32 s25, s23, 0
	v_pk_mul_f32 v[34:35], v[34:35], v[150:151] op_sel_hi:[1,0]
	v_pk_mul_f32 v[32:33], v[32:33], v[150:151] op_sel_hi:[1,0]
	v_pk_mul_f32 v[38:39], v[38:39], v[150:151] op_sel_hi:[1,0]
	v_pk_mul_f32 v[36:37], v[36:37], v[150:151] op_sel_hi:[1,0]
	v_pk_mul_f32 v[78:79], v[78:79], v[150:151] op_sel_hi:[1,0]
	v_pk_mul_f32 v[76:77], v[76:77], v[150:151] op_sel_hi:[1,0]
	v_pk_mul_f32 v[82:83], v[82:83], v[150:151] op_sel_hi:[1,0]
	v_pk_mul_f32 v[80:81], v[80:81], v[150:151] op_sel_hi:[1,0]
	s_add_u32 s0, s0, 0x10180
	v_add_u32_e32 v185, s43, v170
	s_addc_u32 s1, s1, 0
	s_add_i32 s84, s29, 0xc000
	v_lshl_add_u64 v[150:151], s[60:61], 0, v[136:137]
	s_mov_b32 m0, s84
	s_add_i32 s83, s29, 0xe000
	ds_read_b128 v[162:165], v230
	ds_read_b128 v[166:169], v230 offset:1024
	ds_read_b128 v[174:177], v230 offset:2048
	ds_read_b128 v[178:181], v230 offset:3072
	ds_read_b128 v[186:189], v230 offset:4096
	ds_read_b128 v[190:193], v230 offset:5120
	ds_read_b128 v[194:197], v230 offset:6144
	ds_read_b128 v[198:201], v230 offset:7168
	global_load_lds_dwordx4 v[150:151], off
	v_lshl_add_u64 v[150:151], s[60:61], 0, v[138:139]
	s_mov_b32 m0, s83
	v_add_u32_e32 v218, s74, v170
	global_load_lds_dwordx4 v[150:151], off
	s_waitcnt lgkmcnt(8)
	s_barrier
	s_waitcnt lgkmcnt(0)
	v_add_u32_e32 v170, s75, v170
	s_nop 0
	s_waitcnt lgkmcnt(0)
	v_mfma_f32_16x16x32_bf16 v[108:111], v[128:131], v[162:165], v[108:111]
	v_mfma_f32_16x16x32_bf16 v[120:123], v[128:131], v[174:177], v[120:123]
	v_mfma_f32_16x16x32_bf16 v[124:127], v[154:157], v[174:177], v[124:127]
	v_mfma_f32_16x16x32_bf16 v[8:11], v[128:131], v[186:189], v[8:11]
	v_mfma_f32_16x16x32_bf16 v[12:15], v[154:157], v[186:189], v[12:15]
	v_mfma_f32_16x16x32_bf16 v[0:3], v[128:131], v[194:197], v[0:3]
	v_mfma_f32_16x16x32_bf16 v[4:7], v[154:157], v[194:197], v[4:7]
	v_mfma_f32_16x16x32_bf16 v[108:111], v[132:135], v[166:169], v[108:111]
	v_mfma_f32_16x16x32_bf16 v[112:115], v[154:157], v[162:165], v[112:115]
	v_mfma_f32_16x16x32_bf16 v[120:123], v[132:135], v[178:181], v[120:123]
	v_mfma_f32_16x16x32_bf16 v[124:127], v[158:161], v[178:181], v[124:127]
	v_mfma_f32_16x16x32_bf16 v[8:11], v[132:135], v[190:193], v[8:11]
	v_mfma_f32_16x16x32_bf16 v[12:15], v[158:161], v[190:193], v[12:15]
	v_mfma_f32_16x16x32_bf16 v[0:3], v[132:135], v[198:201], v[0:3]
	v_mfma_f32_16x16x32_bf16 v[4:7], v[158:161], v[198:201], v[4:7]
	v_mfma_f32_16x16x32_bf16 v[112:115], v[158:161], v[166:169], v[112:115]
	s_nop 0
	s_barrier
	s_add_i32 s60, s82, s19
	v_lshl_add_u64 v[150:151], v[148:149], 0, s[12:13]
	s_mov_b32 m0, s60
	ds_read_b128 v[202:205], v185
	ds_read_b128 v[206:209], v185 offset:1024
	ds_read_b128 v[210:213], v185 offset:2048
	ds_read_b128 v[214:217], v185 offset:3072
	global_load_lds_dwordx4 v[150:151], off
	v_lshl_add_u64 v[150:151], v[146:147], 0, s[12:13]
	s_add_i32 m0, s60, 0x2000
	s_nop 0
	global_load_lds_dwordx4 v[150:151], off
	s_barrier
	s_waitcnt lgkmcnt(0)
	s_nop 0
	s_waitcnt lgkmcnt(0)
	v_mfma_f32_16x16x32_bf16 v[100:103], v[202:205], v[162:165], v[100:103]
	v_mfma_f32_16x16x32_bf16 v[104:107], v[210:213], v[162:165], v[104:107]
	v_mfma_f32_16x16x32_bf16 v[56:59], v[210:213], v[174:177], v[56:59]
	v_mfma_f32_16x16x32_bf16 v[40:43], v[202:205], v[186:189], v[40:43]
	v_mfma_f32_16x16x32_bf16 v[44:47], v[210:213], v[186:189], v[44:47]
	v_mfma_f32_16x16x32_bf16 v[24:27], v[202:205], v[194:197], v[24:27]
	v_mfma_f32_16x16x32_bf16 v[28:31], v[210:213], v[194:197], v[28:31]
	v_mfma_f32_16x16x32_bf16 v[100:103], v[206:209], v[166:169], v[100:103]
	v_mfma_f32_16x16x32_bf16 v[104:107], v[214:217], v[166:169], v[104:107]
	v_mfma_f32_16x16x32_bf16 v[116:119], v[202:205], v[174:177], v[116:119]
	v_mfma_f32_16x16x32_bf16 v[56:59], v[214:217], v[178:181], v[56:59]
	v_mfma_f32_16x16x32_bf16 v[40:43], v[206:209], v[190:193], v[40:43]
	v_mfma_f32_16x16x32_bf16 v[44:47], v[214:217], v[190:193], v[44:47]
	v_mfma_f32_16x16x32_bf16 v[24:27], v[206:209], v[198:201], v[24:27]
	v_mfma_f32_16x16x32_bf16 v[28:31], v[214:217], v[198:201], v[28:31]
	v_mfma_f32_16x16x32_bf16 v[116:119], v[206:209], v[178:181], v[116:119]
	s_nop 0
	s_mov_b32 m0, s29
	v_lshl_add_u64 v[150:151], v[142:143], 0, s[12:13]
	s_barrier
	ds_read_b128 v[162:165], v230 offset:16384
	ds_read_b128 v[166:169], v230 offset:17408
	ds_read_b128 v[174:177], v230 offset:18432
	ds_read_b128 v[178:181], v230 offset:19456
	ds_read_b128 v[186:189], v230 offset:20480
	ds_read_b128 v[190:193], v230 offset:21504
	ds_read_b128 v[194:197], v230 offset:22528
	ds_read_b128 v[198:201], v230 offset:23552
	global_load_lds_dwordx4 v[150:151], off
	v_lshl_add_u64 v[150:151], v[144:145], 0, s[12:13]
	s_mov_b32 m0, s30
	s_nop 0
	global_load_lds_dwordx4 v[150:151], off
	s_barrier
	s_waitcnt lgkmcnt(0)
	s_nop 0
	s_waitcnt lgkmcnt(0)
	v_mfma_f32_16x16x32_bf16 v[60:63], v[128:131], v[162:165], v[60:63]
	v_mfma_f32_16x16x32_bf16 v[64:67], v[154:157], v[162:165], v[64:67]
	v_mfma_f32_16x16x32_bf16 v[48:51], v[128:131], v[174:177], v[48:51]
	v_mfma_f32_16x16x32_bf16 v[52:55], v[154:157], v[174:177], v[52:55]
	v_mfma_f32_16x16x32_bf16 v[32:35], v[128:131], v[186:189], v[32:35]
	v_mfma_f32_16x16x32_bf16 v[36:39], v[154:157], v[186:189], v[36:39]
	v_mfma_f32_16x16x32_bf16 v[16:19], v[128:131], v[194:197], v[16:19]
	v_mfma_f32_16x16x32_bf16 v[20:23], v[154:157], v[194:197], v[20:23]
	v_mfma_f32_16x16x32_bf16 v[60:63], v[132:135], v[166:169], v[60:63]
	v_mfma_f32_16x16x32_bf16 v[64:67], v[158:161], v[166:169], v[64:67]
	v_mfma_f32_16x16x32_bf16 v[48:51], v[132:135], v[178:181], v[48:51]
	v_mfma_f32_16x16x32_bf16 v[52:55], v[158:161], v[178:181], v[52:55]
	v_mfma_f32_16x16x32_bf16 v[32:35], v[132:135], v[190:193], v[32:35]
	v_mfma_f32_16x16x32_bf16 v[36:39], v[158:161], v[190:193], v[36:39]
	v_mfma_f32_16x16x32_bf16 v[16:19], v[132:135], v[198:201], v[16:19]
	v_mfma_f32_16x16x32_bf16 v[20:23], v[158:161], v[198:201], v[20:23]
	s_nop 0
	s_barrier
	s_add_i32 s19, s43, s19
	v_lshl_add_u64 v[128:129], s[26:27], 0, v[152:153]
	s_mov_b32 m0, s19
	s_nop 0
	global_load_lds_dwordx4 v[128:129], off
	v_lshl_add_u64 v[128:129], s[26:27], 0, v[140:141]
	s_add_i32 m0, s19, 0x2000
	s_nop 0
	global_load_lds_dwordx4 v[128:129], off
	s_waitcnt vmcnt(6)
	s_barrier
	s_nop 0
	v_mfma_f32_16x16x32_bf16 v[84:87], v[202:205], v[174:177], v[84:87]
	v_mfma_f32_16x16x32_bf16 v[88:91], v[210:213], v[174:177], v[88:91]
	v_mfma_f32_16x16x32_bf16 v[76:79], v[202:205], v[186:189], v[76:79]
	v_mfma_f32_16x16x32_bf16 v[80:83], v[210:213], v[186:189], v[80:83]
	v_mfma_f32_16x16x32_bf16 v[68:71], v[202:205], v[194:197], v[68:71]
	v_mfma_f32_16x16x32_bf16 v[72:75], v[210:213], v[194:197], v[72:75]
	v_mfma_f32_16x16x32_bf16 v[92:95], v[202:205], v[162:165], v[92:95]
	v_mfma_f32_16x16x32_bf16 v[96:99], v[210:213], v[162:165], v[96:99]
	v_mfma_f32_16x16x32_bf16 v[84:87], v[206:209], v[178:181], v[84:87]
	v_mfma_f32_16x16x32_bf16 v[88:91], v[214:217], v[178:181], v[88:91]
	v_mfma_f32_16x16x32_bf16 v[76:79], v[206:209], v[190:193], v[76:79]
	v_mfma_f32_16x16x32_bf16 v[80:83], v[214:217], v[190:193], v[80:83]
	v_mfma_f32_16x16x32_bf16 v[68:71], v[206:209], v[198:201], v[68:71]
	v_mfma_f32_16x16x32_bf16 v[72:75], v[214:217], v[198:201], v[72:75]
	v_mfma_f32_16x16x32_bf16 v[92:95], v[206:209], v[166:169], v[92:95]
	v_mfma_f32_16x16x32_bf16 v[96:99], v[214:217], v[166:169], v[96:99]
	s_nop 0
	s_barrier
	ds_read_b128 v[128:131], v218
	ds_read_b128 v[132:135], v218 offset:1024
	ds_read_b128 v[154:157], v218 offset:2048
	ds_read_b128 v[158:161], v218 offset:3072
	s_mov_b32 m0, s28
	v_lshl_add_u64 v[150:151], s[24:25], 0, v[136:137]
	ds_read_b128 v[162:165], v230 offset:32768
	ds_read_b128 v[166:169], v230 offset:33792
	ds_read_b128 v[174:177], v230 offset:34816
	ds_read_b128 v[178:181], v230 offset:35840
	ds_read_b128 v[186:189], v230 offset:36864
	ds_read_b128 v[190:193], v230 offset:37888
	ds_read_b128 v[194:197], v230 offset:38912
	ds_read_b128 v[198:201], v230 offset:39936
	global_load_lds_dwordx4 v[150:151], off
	v_lshl_add_u64 v[150:151], s[24:25], 0, v[138:139]
	s_mov_b32 m0, s3
	s_nop 0
	global_load_lds_dwordx4 v[150:151], off
	s_waitcnt lgkmcnt(8)
	s_barrier
	s_waitcnt lgkmcnt(0)
	s_nop 0
	s_waitcnt lgkmcnt(0)
	v_mfma_f32_16x16x32_bf16 v[108:111], v[128:131], v[162:165], v[108:111]
	v_mfma_f32_16x16x32_bf16 v[120:123], v[128:131], v[174:177], v[120:123]
	v_mfma_f32_16x16x32_bf16 v[124:127], v[154:157], v[174:177], v[124:127]
	v_mfma_f32_16x16x32_bf16 v[8:11], v[128:131], v[186:189], v[8:11]
	v_mfma_f32_16x16x32_bf16 v[12:15], v[154:157], v[186:189], v[12:15]
	v_mfma_f32_16x16x32_bf16 v[0:3], v[128:131], v[194:197], v[0:3]
	v_mfma_f32_16x16x32_bf16 v[4:7], v[154:157], v[194:197], v[4:7]
	v_mfma_f32_16x16x32_bf16 v[108:111], v[132:135], v[166:169], v[108:111]
	v_mfma_f32_16x16x32_bf16 v[112:115], v[154:157], v[162:165], v[112:115]
	v_mfma_f32_16x16x32_bf16 v[120:123], v[132:135], v[178:181], v[120:123]
	v_mfma_f32_16x16x32_bf16 v[124:127], v[158:161], v[178:181], v[124:127]
	v_mfma_f32_16x16x32_bf16 v[8:11], v[132:135], v[190:193], v[8:11]
	v_mfma_f32_16x16x32_bf16 v[12:15], v[158:161], v[190:193], v[12:15]
	v_mfma_f32_16x16x32_bf16 v[0:3], v[132:135], v[198:201], v[0:3]
	v_mfma_f32_16x16x32_bf16 v[4:7], v[158:161], v[198:201], v[4:7]
	v_mfma_f32_16x16x32_bf16 v[112:115], v[158:161], v[166:169], v[112:115]
	s_nop 0
	s_barrier
	s_mov_b32 m0, s81
	v_lshl_add_u64 v[148:149], v[148:149], 0, s[14:15]
	ds_read_b128 v[202:205], v170
	ds_read_b128 v[206:209], v170 offset:1024
	ds_read_b128 v[210:213], v170 offset:2048
	ds_read_b128 v[214:217], v170 offset:3072
	global_load_lds_dwordx4 v[148:149], off
	v_lshl_add_u64 v[146:147], v[146:147], 0, s[14:15]
	s_mov_b32 m0, s51
	s_nop 0
	global_load_lds_dwordx4 v[146:147], off
	s_barrier
	s_waitcnt lgkmcnt(0)
	s_nop 0
	s_waitcnt lgkmcnt(0)
	v_mfma_f32_16x16x32_bf16 v[100:103], v[202:205], v[162:165], v[100:103]
	v_mfma_f32_16x16x32_bf16 v[104:107], v[210:213], v[162:165], v[104:107]
	v_mfma_f32_16x16x32_bf16 v[56:59], v[210:213], v[174:177], v[56:59]
	v_mfma_f32_16x16x32_bf16 v[40:43], v[202:205], v[186:189], v[40:43]
	v_mfma_f32_16x16x32_bf16 v[44:47], v[210:213], v[186:189], v[44:47]
	v_mfma_f32_16x16x32_bf16 v[24:27], v[202:205], v[194:197], v[24:27]
	v_mfma_f32_16x16x32_bf16 v[28:31], v[210:213], v[194:197], v[28:31]
	v_mfma_f32_16x16x32_bf16 v[100:103], v[206:209], v[166:169], v[100:103]
	v_mfma_f32_16x16x32_bf16 v[104:107], v[214:217], v[166:169], v[104:107]
	v_mfma_f32_16x16x32_bf16 v[116:119], v[202:205], v[174:177], v[116:119]
	v_mfma_f32_16x16x32_bf16 v[56:59], v[214:217], v[178:181], v[56:59]
	v_mfma_f32_16x16x32_bf16 v[40:43], v[206:209], v[190:193], v[40:43]
	v_mfma_f32_16x16x32_bf16 v[44:47], v[214:217], v[190:193], v[44:47]
	v_mfma_f32_16x16x32_bf16 v[24:27], v[206:209], v[198:201], v[24:27]
	v_mfma_f32_16x16x32_bf16 v[28:31], v[214:217], v[198:201], v[28:31]
	v_mfma_f32_16x16x32_bf16 v[116:119], v[206:209], v[178:181], v[116:119]
	s_nop 0
	s_mov_b32 m0, s50
	v_lshl_add_u64 v[142:143], v[142:143], 0, s[14:15]
	s_barrier
	ds_read_b128 v[146:149], v230 offset:49152
	ds_read_b128 v[162:165], v230 offset:50176
	ds_read_b128 v[166:169], v230 offset:51200
	ds_read_b128 v[174:177], v230 offset:52224
	ds_read_b128 v[178:181], v230 offset:53248
	ds_read_b128 v[186:189], v230 offset:54272
	ds_read_b128 v[190:193], v230 offset:55296
	ds_read_b128 v[194:197], v230 offset:56320
	global_load_lds_dwordx4 v[142:143], off
	v_lshl_add_u64 v[142:143], v[144:145], 0, s[14:15]
	s_mov_b32 m0, s49
	s_nop 0
	global_load_lds_dwordx4 v[142:143], off
	s_barrier
	s_waitcnt lgkmcnt(0)
	s_nop 0
	s_waitcnt lgkmcnt(0)
	v_mfma_f32_16x16x32_bf16 v[60:63], v[128:131], v[146:149], v[60:63]
	v_mfma_f32_16x16x32_bf16 v[64:67], v[154:157], v[146:149], v[64:67]
	v_mfma_f32_16x16x32_bf16 v[48:51], v[128:131], v[166:169], v[48:51]
	v_mfma_f32_16x16x32_bf16 v[52:55], v[154:157], v[166:169], v[52:55]
	v_mfma_f32_16x16x32_bf16 v[32:35], v[128:131], v[178:181], v[32:35]
	v_mfma_f32_16x16x32_bf16 v[36:39], v[154:157], v[178:181], v[36:39]
	v_mfma_f32_16x16x32_bf16 v[16:19], v[128:131], v[190:193], v[16:19]
	v_mfma_f32_16x16x32_bf16 v[20:23], v[154:157], v[190:193], v[20:23]
	v_mfma_f32_16x16x32_bf16 v[60:63], v[132:135], v[162:165], v[60:63]
	v_mfma_f32_16x16x32_bf16 v[64:67], v[158:161], v[162:165], v[64:67]
	v_mfma_f32_16x16x32_bf16 v[48:51], v[132:135], v[174:177], v[48:51]
	v_mfma_f32_16x16x32_bf16 v[52:55], v[158:161], v[174:177], v[52:55]
	v_mfma_f32_16x16x32_bf16 v[32:35], v[132:135], v[186:189], v[32:35]
	v_mfma_f32_16x16x32_bf16 v[36:39], v[158:161], v[186:189], v[36:39]
	v_mfma_f32_16x16x32_bf16 v[16:19], v[132:135], v[194:197], v[16:19]
	v_mfma_f32_16x16x32_bf16 v[20:23], v[158:161], v[194:197], v[20:23]
	s_nop 0
	s_barrier
	s_mov_b32 m0, s31
	v_lshl_add_u64 v[128:129], s[0:1], 0, v[152:153]
	global_load_lds_dwordx4 v[128:129], off
	v_lshl_add_u64 v[128:129], s[0:1], 0, v[140:141]
	s_mov_b32 m0, s48
	s_nop 0
	global_load_lds_dwordx4 v[128:129], off
	s_waitcnt vmcnt(6)
	s_barrier
	s_nop 0
	v_mfma_f32_16x16x32_bf16 v[84:87], v[202:205], v[166:169], v[84:87]
	v_mfma_f32_16x16x32_bf16 v[88:91], v[210:213], v[166:169], v[88:91]
	v_mfma_f32_16x16x32_bf16 v[76:79], v[202:205], v[178:181], v[76:79]
	v_mfma_f32_16x16x32_bf16 v[80:83], v[210:213], v[178:181], v[80:83]
	v_mfma_f32_16x16x32_bf16 v[68:71], v[202:205], v[190:193], v[68:71]
	v_mfma_f32_16x16x32_bf16 v[72:75], v[210:213], v[190:193], v[72:75]
	v_mfma_f32_16x16x32_bf16 v[92:95], v[202:205], v[146:149], v[92:95]
	v_mfma_f32_16x16x32_bf16 v[96:99], v[210:213], v[146:149], v[96:99]
	v_mfma_f32_16x16x32_bf16 v[84:87], v[206:209], v[174:177], v[84:87]
	v_mfma_f32_16x16x32_bf16 v[88:91], v[214:217], v[174:177], v[88:91]
	v_mfma_f32_16x16x32_bf16 v[76:79], v[206:209], v[186:189], v[76:79]
	v_mfma_f32_16x16x32_bf16 v[80:83], v[214:217], v[186:189], v[80:83]
	v_mfma_f32_16x16x32_bf16 v[68:71], v[206:209], v[194:197], v[68:71]
	v_mfma_f32_16x16x32_bf16 v[72:75], v[214:217], v[194:197], v[72:75]
	v_mfma_f32_16x16x32_bf16 v[92:95], v[206:209], v[162:165], v[92:95]
	v_mfma_f32_16x16x32_bf16 v[96:99], v[214:217], v[162:165], v[96:99]
	s_nop 0
	s_add_u32 s0, s22, 0x10180
	s_addc_u32 s1, s23, 0
	s_mov_b32 m0, s84
	v_lshl_add_u64 v[136:137], s[0:1], 0, v[136:137]
	s_barrier
	ds_read_b128 v[128:131], v171
	ds_read_b128 v[132:135], v171 offset:1024
	ds_read_b128 v[140:143], v171 offset:2048
	ds_read_b128 v[144:147], v171 offset:3072
	ds_read_b128 v[148:151], v230
	ds_read_b128 v[154:157], v230 offset:1024
	ds_read_b128 v[158:161], v230 offset:2048
	ds_read_b128 v[162:165], v230 offset:3072
	ds_read_b128 v[166:169], v230 offset:4096
	ds_read_b128 v[174:177], v230 offset:5120
	ds_read_b128 v[178:181], v230 offset:6144
	ds_read_b128 v[186:189], v230 offset:7168
	global_load_lds_dwordx4 v[136:137], off
	v_lshl_add_u64 v[136:137], s[0:1], 0, v[138:139]
	s_mov_b32 m0, s83
	s_nop 0
	global_load_lds_dwordx4 v[136:137], off
	s_barrier
	s_waitcnt lgkmcnt(0)
	s_nop 0
	s_waitcnt lgkmcnt(0)
	v_mfma_f32_16x16x32_bf16 v[108:111], v[128:131], v[148:151], v[108:111]
	v_mfma_f32_16x16x32_bf16 v[120:123], v[128:131], v[158:161], v[120:123]
	v_mfma_f32_16x16x32_bf16 v[124:127], v[140:143], v[158:161], v[124:127]
	v_mfma_f32_16x16x32_bf16 v[8:11], v[128:131], v[166:169], v[8:11]
	v_mfma_f32_16x16x32_bf16 v[12:15], v[140:143], v[166:169], v[12:15]
	v_mfma_f32_16x16x32_bf16 v[0:3], v[128:131], v[178:181], v[0:3]
	v_mfma_f32_16x16x32_bf16 v[4:7], v[140:143], v[178:181], v[4:7]
	v_mfma_f32_16x16x32_bf16 v[108:111], v[132:135], v[154:157], v[108:111]
	v_mfma_f32_16x16x32_bf16 v[112:115], v[140:143], v[148:151], v[112:115]
	v_mfma_f32_16x16x32_bf16 v[120:123], v[132:135], v[162:165], v[120:123]
	v_mfma_f32_16x16x32_bf16 v[124:127], v[144:147], v[162:165], v[124:127]
	v_mfma_f32_16x16x32_bf16 v[8:11], v[132:135], v[174:177], v[8:11]
	v_mfma_f32_16x16x32_bf16 v[12:15], v[144:147], v[174:177], v[12:15]
	v_mfma_f32_16x16x32_bf16 v[0:3], v[132:135], v[186:189], v[0:3]
	v_mfma_f32_16x16x32_bf16 v[4:7], v[144:147], v[186:189], v[4:7]
	v_mfma_f32_16x16x32_bf16 v[112:115], v[144:147], v[154:157], v[112:115]
	s_nop 0
	s_barrier
	ds_read_b128 v[136:139], v185
	ds_read_b128 v[190:193], v185 offset:1024
	ds_read_b128 v[194:197], v185 offset:2048
	ds_read_b128 v[198:201], v185 offset:3072
	s_barrier
	s_waitcnt lgkmcnt(0)
	s_nop 0
	s_waitcnt lgkmcnt(0)
	v_mfma_f32_16x16x32_bf16 v[100:103], v[136:139], v[148:151], v[100:103]
	v_mfma_f32_16x16x32_bf16 v[104:107], v[194:197], v[148:151], v[104:107]
	v_mfma_f32_16x16x32_bf16 v[56:59], v[194:197], v[158:161], v[56:59]
	v_mfma_f32_16x16x32_bf16 v[40:43], v[136:139], v[166:169], v[40:43]
	v_mfma_f32_16x16x32_bf16 v[44:47], v[194:197], v[166:169], v[44:47]
	v_mfma_f32_16x16x32_bf16 v[24:27], v[136:139], v[178:181], v[24:27]
	v_mfma_f32_16x16x32_bf16 v[100:103], v[190:193], v[154:157], v[100:103]
	v_mfma_f32_16x16x32_bf16 v[104:107], v[198:201], v[154:157], v[104:107]
	v_mfma_f32_16x16x32_bf16 v[116:119], v[136:139], v[158:161], v[116:119]
	v_mfma_f32_16x16x32_bf16 v[56:59], v[198:201], v[162:165], v[56:59]
	v_mfma_f32_16x16x32_bf16 v[40:43], v[190:193], v[174:177], v[40:43]
	v_mfma_f32_16x16x32_bf16 v[44:47], v[198:201], v[174:177], v[44:47]
	v_mfma_f32_16x16x32_bf16 v[24:27], v[190:193], v[186:189], v[24:27]
	v_mfma_f32_16x16x32_bf16 v[28:31], v[194:197], v[178:181], v[28:31]
	v_mfma_f32_16x16x32_bf16 v[116:119], v[190:193], v[162:165], v[116:119]
	v_mfma_f32_16x16x32_bf16 v[154:157], v[198:201], v[186:189], v[28:31]
	s_nop 0
	s_barrier
	s_nop 3
	ds_read_b128 v[28:31], v230 offset:16384
	ds_read_b128 v[148:151], v230 offset:17408
	ds_read_b128 v[158:161], v230 offset:18432
	ds_read_b128 v[162:165], v230 offset:19456
	ds_read_b128 v[166:169], v230 offset:20480
	ds_read_b128 v[174:177], v230 offset:21504
	ds_read_b128 v[178:181], v230 offset:22528
	ds_read_b128 v[186:189], v230 offset:23552
	s_waitcnt vmcnt(4)
	s_barrier
	s_waitcnt lgkmcnt(0)
	s_nop 0
	s_waitcnt lgkmcnt(0)
	v_mfma_f32_16x16x32_bf16 v[60:63], v[128:131], v[28:31], v[60:63]
	v_mfma_f32_16x16x32_bf16 v[64:67], v[140:143], v[28:31], v[64:67]
	v_mfma_f32_16x16x32_bf16 v[48:51], v[128:131], v[158:161], v[48:51]
	v_mfma_f32_16x16x32_bf16 v[52:55], v[140:143], v[158:161], v[52:55]
	v_mfma_f32_16x16x32_bf16 v[32:35], v[128:131], v[166:169], v[32:35]
	v_mfma_f32_16x16x32_bf16 v[36:39], v[140:143], v[166:169], v[36:39]
	v_mfma_f32_16x16x32_bf16 v[16:19], v[128:131], v[178:181], v[16:19]
	v_mfma_f32_16x16x32_bf16 v[60:63], v[132:135], v[148:151], v[60:63]
	v_mfma_f32_16x16x32_bf16 v[64:67], v[144:147], v[148:151], v[64:67]
	v_mfma_f32_16x16x32_bf16 v[48:51], v[132:135], v[162:165], v[48:51]
	v_mfma_f32_16x16x32_bf16 v[52:55], v[144:147], v[162:165], v[52:55]
	v_mfma_f32_16x16x32_bf16 v[32:35], v[132:135], v[174:177], v[32:35]
	v_mfma_f32_16x16x32_bf16 v[36:39], v[144:147], v[174:177], v[36:39]
	v_mfma_f32_16x16x32_bf16 v[132:135], v[132:135], v[186:189], v[16:19]
	v_mfma_f32_16x16x32_bf16 v[16:19], v[140:143], v[178:181], v[20:23]
	v_mfma_f32_16x16x32_bf16 v[202:205], v[144:147], v[186:189], v[16:19]
	s_nop 0
	s_nop 0
	v_mfma_f32_16x16x32_bf16 v[16:19], v[136:139], v[28:31], v[92:95]
	v_mfma_f32_16x16x32_bf16 v[92:95], v[190:193], v[148:151], v[16:19]
	v_mfma_f32_16x16x32_bf16 v[16:19], v[194:197], v[28:31], v[96:99]
	v_mfma_f32_16x16x32_bf16 v[96:99], v[198:201], v[148:151], v[16:19]
	v_mfma_f32_16x16x32_bf16 v[16:19], v[136:139], v[158:161], v[84:87]
	v_mfma_f32_16x16x32_bf16 v[206:209], v[190:193], v[162:165], v[16:19]
	v_mfma_f32_16x16x32_bf16 v[16:19], v[194:197], v[158:161], v[88:91]
	v_mfma_f32_16x16x32_bf16 v[158:161], v[198:201], v[162:165], v[16:19]
	v_mfma_f32_16x16x32_bf16 v[16:19], v[136:139], v[166:169], v[76:79]
	v_mfma_f32_16x16x32_bf16 v[162:165], v[190:193], v[174:177], v[16:19]
	v_mfma_f32_16x16x32_bf16 v[16:19], v[194:197], v[166:169], v[80:83]
	v_mfma_f32_16x16x32_bf16 v[166:169], v[198:201], v[174:177], v[16:19]
	v_mfma_f32_16x16x32_bf16 v[16:19], v[136:139], v[178:181], v[68:71]
	v_mfma_f32_16x16x32_bf16 v[136:139], v[190:193], v[186:189], v[16:19]
	v_mfma_f32_16x16x32_bf16 v[16:19], v[194:197], v[178:181], v[72:75]
	v_mfma_f32_16x16x32_bf16 v[174:177], v[198:201], v[186:189], v[16:19]
	s_nop 0
	s_barrier
	ds_read_b128 v[68:71], v218
	ds_read_b128 v[178:181], v218 offset:1024
	ds_read_b128 v[186:189], v218 offset:2048
	ds_read_b128 v[190:193], v218 offset:3072
	ds_read_b128 v[72:75], v230 offset:32768
	ds_read_b128 v[76:79], v230 offset:33792
	ds_read_b128 v[80:83], v230 offset:34816
	ds_read_b128 v[84:87], v230 offset:35840
	ds_read_b128 v[194:197], v230 offset:36864
	ds_read_b128 v[198:201], v230 offset:37888
	ds_read_b128 v[210:213], v230 offset:38912
	ds_read_b128 v[214:217], v230 offset:39936
	s_waitcnt vmcnt(2)
	s_barrier
	s_waitcnt lgkmcnt(0)
	s_nop 0
	s_waitcnt lgkmcnt(0)
	v_mfma_f32_16x16x32_bf16 v[16:19], v[68:71], v[72:75], v[108:111]
	v_mfma_f32_16x16x32_bf16 v[148:151], v[178:181], v[76:79], v[16:19]
	v_mfma_f32_16x16x32_bf16 v[16:19], v[186:189], v[72:75], v[112:115]
	v_mfma_f32_16x16x32_bf16 v[28:31], v[190:193], v[76:79], v[16:19]
	v_mfma_f32_16x16x32_bf16 v[16:19], v[68:71], v[80:83], v[120:123]
	v_mfma_f32_16x16x32_bf16 v[8:11], v[68:71], v[194:197], v[8:11]
	v_mfma_f32_16x16x32_bf16 v[0:3], v[68:71], v[210:213], v[0:3]
	v_mfma_f32_16x16x32_bf16 v[128:131], v[178:181], v[84:87], v[16:19]
	v_mfma_f32_16x16x32_bf16 v[16:19], v[186:189], v[80:83], v[124:127]
	v_mfma_f32_16x16x32_bf16 v[108:111], v[178:181], v[198:201], v[8:11]
	v_mfma_f32_16x16x32_bf16 v[8:11], v[186:189], v[194:197], v[12:15]
	v_mfma_f32_16x16x32_bf16 v[88:91], v[178:181], v[214:217], v[0:3]
	v_mfma_f32_16x16x32_bf16 v[0:3], v[186:189], v[210:213], v[4:7]
	v_mfma_f32_16x16x32_bf16 v[20:23], v[190:193], v[84:87], v[16:19]
	v_mfma_f32_16x16x32_bf16 v[16:19], v[190:193], v[198:201], v[8:11]
	v_mfma_f32_16x16x32_bf16 v[8:11], v[190:193], v[214:217], v[0:3]
	s_nop 0
	s_barrier
	ds_read_b128 v[112:115], v170
	ds_read_b128 v[218:221], v170 offset:1024
	ds_read_b128 v[222:225], v170 offset:2048
	ds_read_b128 v[226:229], v170 offset:3072
	s_waitcnt vmcnt(0)
	s_barrier
	s_waitcnt lgkmcnt(0)
	s_nop 0
	s_waitcnt lgkmcnt(0)
	v_mfma_f32_16x16x32_bf16 v[0:3], v[112:115], v[72:75], v[100:103]
	v_mfma_f32_16x16x32_bf16 v[144:147], v[218:221], v[76:79], v[0:3]
	v_mfma_f32_16x16x32_bf16 v[0:3], v[222:225], v[72:75], v[104:107]
	v_mfma_f32_16x16x32_bf16 v[140:143], v[226:229], v[76:79], v[0:3]
	v_mfma_f32_16x16x32_bf16 v[0:3], v[112:115], v[80:83], v[116:119]
	v_mfma_f32_16x16x32_bf16 v[124:127], v[218:221], v[84:87], v[0:3]
	v_mfma_f32_16x16x32_bf16 v[0:3], v[222:225], v[80:83], v[56:59]
	v_mfma_f32_16x16x32_bf16 v[120:123], v[226:229], v[84:87], v[0:3]
	v_mfma_f32_16x16x32_bf16 v[0:3], v[112:115], v[194:197], v[40:43]
	v_mfma_f32_16x16x32_bf16 v[104:107], v[218:221], v[198:201], v[0:3]
	v_mfma_f32_16x16x32_bf16 v[0:3], v[222:225], v[194:197], v[44:47]
	v_mfma_f32_16x16x32_bf16 v[100:103], v[226:229], v[198:201], v[0:3]
	v_mfma_f32_16x16x32_bf16 v[0:3], v[112:115], v[210:213], v[24:27]
	v_mfma_f32_16x16x32_bf16 v[84:87], v[218:221], v[214:217], v[0:3]
	v_mfma_f32_16x16x32_bf16 v[0:3], v[222:225], v[210:213], v[154:157]
	v_mfma_f32_16x16x32_bf16 v[80:83], v[226:229], v[214:217], v[0:3]
	s_nop 0
	s_barrier
	ds_read_b128 v[44:47], v230 offset:49152
	ds_read_b128 v[56:59], v230 offset:50176
	ds_read_b128 v[116:119], v230 offset:51200
	ds_read_b128 v[154:157], v230 offset:52224
	ds_read_b128 v[194:197], v230 offset:53248
	ds_read_b128 v[198:201], v230 offset:54272
	ds_read_b128 v[210:213], v230 offset:55296
	ds_read_b128 v[214:217], v230 offset:56320
	s_barrier
	s_waitcnt lgkmcnt(0)
	s_nop 0
	s_waitcnt lgkmcnt(0)
	v_mfma_f32_16x16x32_bf16 v[0:3], v[68:71], v[44:47], v[60:63]
	v_mfma_f32_16x16x32_bf16 v[76:79], v[178:181], v[56:59], v[0:3]
	v_mfma_f32_16x16x32_bf16 v[0:3], v[186:189], v[44:47], v[64:67]
	v_mfma_f32_16x16x32_bf16 v[72:75], v[190:193], v[56:59], v[0:3]
	v_mfma_f32_16x16x32_bf16 v[0:3], v[68:71], v[116:119], v[48:51]
	v_mfma_f32_16x16x32_bf16 v[64:67], v[178:181], v[154:157], v[0:3]
	v_mfma_f32_16x16x32_bf16 v[0:3], v[186:189], v[116:119], v[52:55]
	v_mfma_f32_16x16x32_bf16 v[12:15], v[190:193], v[154:157], v[0:3]
	v_mfma_f32_16x16x32_bf16 v[0:3], v[68:71], v[194:197], v[32:35]
	v_mfma_f32_16x16x32_bf16 v[52:55], v[178:181], v[198:201], v[0:3]
	v_mfma_f32_16x16x32_bf16 v[0:3], v[186:189], v[194:197], v[36:39]
	v_mfma_f32_16x16x32_bf16 v[4:7], v[190:193], v[198:201], v[0:3]
	v_mfma_f32_16x16x32_bf16 v[0:3], v[68:71], v[210:213], v[132:135]
	v_mfma_f32_16x16x32_bf16 v[40:43], v[178:181], v[214:217], v[0:3]
	v_mfma_f32_16x16x32_bf16 v[0:3], v[186:189], v[210:213], v[202:205]
	v_mfma_f32_16x16x32_bf16 v[0:3], v[190:193], v[214:217], v[0:3]
	s_nop 0
	s_nop 0
	v_mfma_f32_16x16x32_bf16 v[32:35], v[222:225], v[44:47], v[96:99]
	v_mfma_f32_16x16x32_bf16 v[68:71], v[226:229], v[56:59], v[32:35]
	v_mfma_f32_16x16x32_bf16 v[32:35], v[112:115], v[116:119], v[206:209]
	v_mfma_f32_16x16x32_bf16 v[24:27], v[112:115], v[44:47], v[92:95]
	v_mfma_f32_16x16x32_bf16 v[60:63], v[218:221], v[154:157], v[32:35]
	v_mfma_f32_16x16x32_bf16 v[32:35], v[222:225], v[116:119], v[158:161]
	v_mfma_f32_16x16x32_bf16 v[24:27], v[218:221], v[56:59], v[24:27]
	v_mfma_f32_16x16x32_bf16 v[56:59], v[226:229], v[154:157], v[32:35]
	v_mfma_f32_16x16x32_bf16 v[32:35], v[112:115], v[194:197], v[162:165]
	v_mfma_f32_16x16x32_bf16 v[48:51], v[218:221], v[198:201], v[32:35]
	v_mfma_f32_16x16x32_bf16 v[32:35], v[222:225], v[194:197], v[166:169]
	v_mfma_f32_16x16x32_bf16 v[44:47], v[226:229], v[198:201], v[32:35]
	v_mfma_f32_16x16x32_bf16 v[32:35], v[112:115], v[210:213], v[136:139]
	v_mfma_f32_16x16x32_bf16 v[36:39], v[218:221], v[214:217], v[32:35]
	v_mfma_f32_16x16x32_bf16 v[32:35], v[222:225], v[210:213], v[174:177]
	v_mfma_f32_16x16x32_bf16 v[32:35], v[226:229], v[214:217], v[32:35]
	s_nop 0
	s_cmpk_gt_u32 s2, 0xff
	s_barrier
	s_cbranch_scc1 .LBB0_663
	s_barrier
